# mLSTM prep serial section (readlane chain + DPP scans) and scan-step LDS fragment reads issued two tiles ahead; on top of 8-wave forward substitution
# speedup vs baseline: 1.0300x; 1.0123x over previous
; template <bool GDN, int NT> __device__ __forceinline__ void scan_load(const Frame& F, int b, int h, int dir, const ScanLane& L, int s, ScanOps<NT>& o) {
;     const int cidx = dir ? (s < 4 ? 3 - s : 39 - s) : s;
;     const int ud = ((b * 4 + h) * 36 + cidx) * 2 + dir;
;     if (GDN) {
;         const char* base = (const char*)F.PG + (size_t)ud * 32768;
;         const char* bM = upin(base); const char* bB = upin(base + 8192); const char* bQ = upin(base + 16384); const char* bO = upin(base + 24576);
; #pragma unroll
;         for (int ks = 0; ks < 2; ++ks) { o.Mf[ks] = ldun<bf16x8>(bM + ks * 1024, L.o16); o.Qf[ks] = ldun<bf16x8>(bQ + ks * 1024, L.o16); }
; #pragma unroll
;         for (int pr = 0; pr < 2; ++pr) { const v4u qb = ldun<v4u>(bB + pr * 1024, L.o16p), qo = ldun<v4u>(bO + pr * 1024, L.o16p);
;             o.bv[2 * pr] = (v2u){qb.x, qb.y}; o.bv[2 * pr + 1] = (v2u){qb.z, qb.w}; o.ov[2 * pr] = (v2u){qo.x, qo.y}; o.ov[2 * pr + 1] = (v2u){qo.z, qo.w}; }
;         o.wi = (f32x4){1.f, 1.f, 1.f, 1.f};
;     } else {
;         const char* zq = upin((const char*)F.Z + ((size_t)chunk_row0(b, cidx) * ZW + ZC_LQ + h * 64) * 2);
; #pragma unroll
;         for (int ks = 0; ks < 2; ++ks) { o.Qf[ks] = ldu<bf16x8>(zq + ks * 64, L.zq); o.Mf[ks] = o.Qf[ks]; }
;         const char* base = (const char*)F.PM + (size_t)ud * 20480;
;         const char* bO = upin(base); const char* bB = upin(base + 10240);
; #pragma unroll
;         for (int pr = 0; pr < 2; ++pr) { const v4u qb = ldun<v4u>(bB + pr * 1024, L.o16p), qo = ldun<v4u>(bO + pr * 1024, L.o16p);
;             o.bv[2 * pr] = (v2u){qb.x, qb.y}; o.bv[2 * pr + 1] = (v2u){qb.z, qb.w}; o.ov[2 * pr] = (v2u){qo.x, qo.y}; o.ov[2 * pr + 1] = (v2u){qo.z, qo.w}; }
;         o.bv[4] = ldun<v2u>(bB + 2048, L.o8); o.ov[4] = ldun<v2u>(bO + 2048, L.o8);
;         o.wi = ldu<f32x4>(upin((const char*)F.WI + (size_t)ud * 256), L.wi);
;     }
;     ...
;     const float gl = ((const LAS float*)(St + 4 * 80 * 72))[(dir ? (s < 4 ? 3 - s : 39 - s) : s) * 2 + dir];
;     f32x4 O[NT];
; #pragma unroll
;     for (int t = 0; t < NT; ++t) {
;         const LAS bf16_t* sp2 = Sb + (16 * t + lr) * 72 + 8 * lq;
;         const bf16x8 s0 = *(const LAS bf16x8*)sp2, s1 = *(const LAS bf16x8*)(sp2 + 32);
;         const f32x4 bv = unpack4(use.bv[t]), ov = unpack4(use.ov[t]);
;         if (GDN) {
;             f32x4 o = ov, sn = S[t] * gl + bv;
.LBB0_346:
	s_add_i32 s0, s25, 5
	s_min_u32 s3, s0, 33
	s_add_i32 s6, s3, 2
	s_sub_i32 s3, 37, s3
	s_and_b64 s[4:5], s[90:91], exec
	s_cselect_b32 s3, s6, s3
	s_lshl_b32 s4, s3, 6
	s_add_i32 s4, s4, s33
	s_add_i32 s3, s3, s31
	s_mulk_i32 s4, 0xd00
	s_lshl_b32 s3, s3, 1
	s_or_b32 s4, s36, s4
	s_mov_b32 s5, s37
	s_add_i32 s92, s3, s68
	s_lshl_b64 s[4:5], s[4:5], 1
	s_add_u32 s4, s16, s4
	s_addc_u32 s5, s17, s5
	global_load_dwordx4 v[24:27], v28, s[4:5]
	global_load_dwordx4 v[20:23], v28, s[4:5] offset:64
	s_mul_i32 s4, s92, 0x5000
	v_readlane_b32 s5, v254, 46
	s_mul_hi_u32 s3, s92, 0x5000
	s_add_u32 s4, s5, s4
	v_readlane_b32 s5, v254, 47
	s_addc_u32 s5, s5, s3
	s_mov_b64 s[6:7], s[4:5]
	s_add_u32 s4, s4, 0x2800
	s_addc_u32 s5, s5, 0
	s_nop 0
	global_load_dwordx4 v[44:47], v32, s[4:5] nt
	global_load_dwordx4 v[28:31], v32, s[4:5] offset:1024 nt
	global_load_dwordx4 v[52:55], v32, s[6:7] nt
	s_nop 0
	global_load_dwordx4 v[32:35], v32, s[6:7] offset:1024 nt
	s_nop 0
	global_load_dwordx2 v[140:141], v100, s[4:5] offset:2048 nt
	global_load_dwordx2 v[138:139], v100, s[6:7] offset:2048 nt
	s_lshl_b64 s[4:5], s[92:93], 8
	v_readlane_b32 s6, v254, 52
	v_readlane_b32 s7, v254, 53
	s_add_u32 s4, s6, s4
	s_addc_u32 s5, s7, s5
	s_add_i32 s3, s24, 37
	v_lshl_add_u64 v[184:185], s[4:5], 0, v[0:1]
	s_and_b64 s[4:5], s[90:91], exec
	s_cselect_b32 s0, s0, s3
	s_lshl_b32 s0, s0, 3
	s_add_i32 s0, s34, s0
	v_mov_b32_e32 v0, s0
	ds_read_b32 v0, v0 offset:46080
	ds_read_b128 v[100:103], v203 offset:11520
	ds_read_b128 v[104:107], v203 offset:11584
	ds_read_b128 v[212:215], v203 offset:13824
	ds_read_b128 v[216:219], v203 offset:13888
	ds_read_b128 v[224:227], v203 offset:16128
	ds_read_b128 v[242:245], v203 offset:16192
	s_waitcnt lgkmcnt(5)
	v_mfma_f32_16x16x32_bf16 v[100:103], v[56:59], v[100:103], 0
	s_waitcnt vmcnt(63)
	v_lshlrev_b32_e32 v108, 16, v84
	v_and_b32_e32 v109, 0xffff0000, v84
	v_lshlrev_b32_e32 v110, 16, v85
	s_waitcnt lgkmcnt(4)
	v_mfma_f32_16x16x32_bf16 v[100:103], v[48:51], v[104:107], v[100:103]
	v_and_b32_e32 v111, 0xffff0000, v85
	s_waitcnt vmcnt(63)
	v_lshlrev_b32_e32 v112, 16, v88
	v_and_b32_e32 v113, 0xffff0000, v88
	v_lshlrev_b32_e32 v114, 16, v89
	v_and_b32_e32 v115, 0xffff0000, v89
	v_pk_fma_f32 v[150:151], v[192:193], v[0:1], v[110:111] op_sel_hi:[1,0,1]
	v_pk_fma_f32 v[148:149], v[190:191], v[0:1], v[108:109] op_sel_hi:[1,0,1]
	s_waitcnt vmcnt(63)
	v_pk_fma_f32 v[108:109], v[74:75], v[102:103], v[114:115]
	v_pk_fma_f32 v[110:111], v[72:73], v[100:101], v[112:113]
	s_waitcnt lgkmcnt(3)
	v_mfma_f32_16x16x32_bf16 v[100:103], v[56:59], v[212:215], 0
	v_lshlrev_b32_e32 v112, 16, v86
	v_and_b32_e32 v113, 0xffff0000, v86
	v_lshlrev_b32_e32 v114, 16, v87
	s_waitcnt lgkmcnt(2)
	v_mfma_f32_16x16x32_bf16 v[100:103], v[48:51], v[216:219], v[100:103]
	ds_read_b128 v[212:215], v203 offset:18432
	ds_read_b128 v[216:219], v203 offset:18496
	v_and_b32_e32 v115, 0xffff0000, v87
	v_lshlrev_b32_e32 v116, 16, v90
	v_and_b32_e32 v117, 0xffff0000, v90
	v_lshlrev_b32_e32 v118, 16, v91
	v_and_b32_e32 v119, 0xffff0000, v91
	v_pk_fma_f32 v[152:153], v[188:189], v[0:1], v[114:115] op_sel_hi:[1,0,1]
	v_pk_fma_f32 v[154:155], v[154:155], v[0:1], v[112:113] op_sel_hi:[1,0,1]
	s_nop 0
	v_pk_fma_f32 v[112:113], v[74:75], v[102:103], v[118:119]
	v_pk_fma_f32 v[114:115], v[72:73], v[100:101], v[116:117]
	s_waitcnt lgkmcnt(3)
	v_mfma_f32_16x16x32_bf16 v[100:103], v[56:59], v[224:227], 0
	v_lshlrev_b32_e32 v116, 16, v76
	v_and_b32_e32 v117, 0xffff0000, v76
	v_lshlrev_b32_e32 v118, 16, v77
	s_waitcnt lgkmcnt(2)
; template <int N> __device__ __forceinline__ float row16_bcast(float v) { return dppf<0x150 + N>(v); }
; __device__ __forceinline__ float frcp(float x) { return __builtin_amdgcn_rcpf(x); }
;     ...
;             o = __builtin_amdgcn_mfma_f32_16x16x32_bf16(use.Qf[0], s0, o, 0, 0, 0); o = __builtin_amdgcn_mfma_f32_16x16x32_bf16(use.Qf[1], s1, o, 0, 0, 0);
;             S[t] = S[t] * gl + bv; O[t] = o * use.wi + ov; }
;     }
;     if (!GDN) {
; #pragma unroll
;         for (int i = 0; i < 4; ++i) { const float den = row16_bcast<0>(O[NT - 1][i]), fl = row16_bcast<1>(O[NT - 1][i]); const float dv = frcp(fmaxf(fabsf(den), fl));
; #pragma unroll
;             for (int t = 0; t < 4; ++t) O[t][i] *= dv; }
;     }
; #pragma unroll
;     for (int t = 0; t < 4; ++t) Oprev[t] = O[t];
	v_mfma_f32_16x16x32_bf16 v[100:103], v[48:51], v[242:245], v[100:103]
	ds_read_b128 v[224:227], v203 offset:20736
	ds_read_b128 v[242:245], v203 offset:20800
	v_and_b32_e32 v119, 0xffff0000, v77
	v_lshlrev_b32_e32 v160, 16, v80
	v_and_b32_e32 v161, 0xffff0000, v80
	v_lshlrev_b32_e32 v166, 16, v81
	v_and_b32_e32 v167, 0xffff0000, v81
	v_pk_fma_f32 v[156:157], v[186:187], v[0:1], v[118:119] op_sel_hi:[1,0,1]
	v_pk_fma_f32 v[158:159], v[182:183], v[0:1], v[116:117] op_sel_hi:[1,0,1]
	s_nop 0
	v_pk_fma_f32 v[116:117], v[74:75], v[102:103], v[166:167]
	v_pk_fma_f32 v[118:119], v[72:73], v[100:101], v[160:161]
	s_waitcnt lgkmcnt(3)
	v_mfma_f32_16x16x32_bf16 v[100:103], v[56:59], v[212:215], 0
	v_lshlrev_b32_e32 v166, 16, v78
	v_and_b32_e32 v167, 0xffff0000, v78
	v_lshlrev_b32_e32 v160, 16, v79
	s_waitcnt lgkmcnt(2)
	v_mfma_f32_16x16x32_bf16 v[100:103], v[48:51], v[216:219], v[100:103]
	v_and_b32_e32 v161, 0xffff0000, v79
	v_lshlrev_b32_e32 v168, 16, v82
	v_and_b32_e32 v169, 0xffff0000, v82
	v_lshlrev_b32_e32 v170, 16, v83
	v_and_b32_e32 v171, 0xffff0000, v83
	v_pk_fma_f32 v[160:161], v[162:163], v[0:1], v[160:161] op_sel_hi:[1,0,1]
	v_pk_fma_f32 v[162:163], v[178:179], v[0:1], v[166:167] op_sel_hi:[1,0,1]
	s_nop 0
	v_pk_fma_f32 v[166:167], v[74:75], v[102:103], v[170:171]
	v_pk_fma_f32 v[168:169], v[72:73], v[100:101], v[168:169]
	s_waitcnt lgkmcnt(1)
	v_mfma_f32_16x16x32_bf16 v[100:103], v[56:59], v[224:227], 0
	v_lshlrev_b32_e32 v174, 16, v2
	v_and_b32_e32 v175, 0xffff0000, v2
	v_lshlrev_b32_e32 v176, 16, v3
	s_waitcnt lgkmcnt(0)
	v_mfma_f32_16x16x32_bf16 v[100:103], v[48:51], v[242:245], v[100:103]
	v_and_b32_e32 v177, 0xffff0000, v3
	v_lshlrev_b32_e32 v170, 16, v144
	v_and_b32_e32 v171, 0xffff0000, v144
	v_lshlrev_b32_e32 v172, 16, v145
	v_and_b32_e32 v173, 0xffff0000, v145
	s_nop 2
	v_pk_fma_f32 v[100:101], v[72:73], v[100:101], v[174:175]
	v_pk_fma_f32 v[102:103], v[74:75], v[102:103], v[176:177]
	v_pk_fma_f32 v[178:179], v[164:165], v[0:1], v[172:173] op_sel_hi:[1,0,1]
	v_mov_b32_dpp v104, v100 row_newbcast:0 row_mask:0xf bank_mask:0xf bound_ctrl:1
	v_mov_b32_dpp v100, v100 row_newbcast:1 row_mask:0xf bank_mask:0xf bound_ctrl:1
	v_max_f32_e32 v100, v100, v100
	v_max_f32_e64 v104, |v104|, |v104|
	v_max_f32_e32 v100, v104, v100
	v_rcp_f32_e32 v100, v100
	v_mov_b32_dpp v104, v101 row_newbcast:0 row_mask:0xf bank_mask:0xf bound_ctrl:1
	v_mov_b32_dpp v101, v101 row_newbcast:1 row_mask:0xf bank_mask:0xf bound_ctrl:1
	v_max_f32_e32 v101, v101, v101
	v_max_f32_e64 v104, |v104|, |v104|
	v_max_f32_e32 v101, v104, v101
	v_rcp_f32_e32 v101, v101
	v_mov_b32_dpp v104, v102 row_newbcast:0 row_mask:0xf bank_mask:0xf bound_ctrl:1
	v_mov_b32_dpp v102, v102 row_newbcast:1 row_mask:0xf bank_mask:0xf bound_ctrl:1
	v_max_f32_e32 v102, v102, v102
	v_max_f32_e64 v104, |v104|, |v104|
	v_max_f32_e32 v102, v104, v102
	v_rcp_f32_e32 v102, v102
	v_mov_b32_dpp v104, v103 row_newbcast:0 row_mask:0xf bank_mask:0xf bound_ctrl:1
	v_mov_b32_dpp v103, v103 row_newbcast:1 row_mask:0xf bank_mask:0xf bound_ctrl:1
	v_max_f32_e32 v103, v103, v103
	v_max_f32_e64 v104, |v104|, |v104|
	v_max_f32_e32 v103, v104, v103
	v_rcp_f32_e32 v103, v103
	v_pk_fma_f32 v[164:165], v[180:181], v[0:1], v[170:171] op_sel_hi:[1,0,1]
	v_pk_mul_f32 v[104:105], v[110:111], v[100:101]
	s_add_i32 s3, s24, -6
	v_pk_mul_f32 v[106:107], v[108:109], v[102:103]
	v_pk_mul_f32 v[108:109], v[114:115], v[100:101]
	v_pk_mul_f32 v[110:111], v[112:113], v[102:103]
	v_pk_mul_f32 v[112:113], v[118:119], v[100:101]
	v_pk_mul_f32 v[114:115], v[116:117], v[102:103]
	v_pk_mul_f32 v[116:117], v[168:169], v[100:101]
	v_pk_mul_f32 v[118:119], v[166:167], v[102:103]
	s_mov_b64 s[20:21], 0
	v_mov_b32_e32 v183, v179
	v_mov_b32_e32 v182, v178
	v_mov_b32_e32 v181, v165
	v_mov_b32_e32 v180, v164

; template <bool GDN, int NT> __device__ __forceinline__ void scan_load(const Frame& F, int b, int h, int dir, const ScanLane& L, int s, ScanOps<NT>& o) {
;     const int cidx = dir ? (s < 4 ? 3 - s : 39 - s) : s;
;     const int ud = ((b * 4 + h) * 36 + cidx) * 2 + dir;
;     if (GDN) {
;         const char* base = (const char*)F.PG + (size_t)ud * 32768;
;         const char* bM = upin(base); const char* bB = upin(base + 8192); const char* bQ = upin(base + 16384); const char* bO = upin(base + 24576);
; #pragma unroll
;         for (int ks = 0; ks < 2; ++ks) { o.Mf[ks] = ldun<bf16x8>(bM + ks * 1024, L.o16); o.Qf[ks] = ldun<bf16x8>(bQ + ks * 1024, L.o16); }
; #pragma unroll
;         for (int pr = 0; pr < 2; ++pr) { const v4u qb = ldun<v4u>(bB + pr * 1024, L.o16p), qo = ldun<v4u>(bO + pr * 1024, L.o16p);
;             o.bv[2 * pr] = (v2u){qb.x, qb.y}; o.bv[2 * pr + 1] = (v2u){qb.z, qb.w}; o.ov[2 * pr] = (v2u){qo.x, qo.y}; o.ov[2 * pr + 1] = (v2u){qo.z, qo.w}; }
;         o.wi = (f32x4){1.f, 1.f, 1.f, 1.f};
;     } else {
;         const char* zq = upin((const char*)F.Z + ((size_t)chunk_row0(b, cidx) * ZW + ZC_LQ + h * 64) * 2);
; #pragma unroll
;         for (int ks = 0; ks < 2; ++ks) { o.Qf[ks] = ldu<bf16x8>(zq + ks * 64, L.zq); o.Mf[ks] = o.Qf[ks]; }
;         const char* base = (const char*)F.PM + (size_t)ud * 20480;
;         const char* bO = upin(base); const char* bB = upin(base + 10240);
; #pragma unroll
;         for (int pr = 0; pr < 2; ++pr) { const v4u qb = ldun<v4u>(bB + pr * 1024, L.o16p), qo = ldun<v4u>(bO + pr * 1024, L.o16p);
;             o.bv[2 * pr] = (v2u){qb.x, qb.y}; o.bv[2 * pr + 1] = (v2u){qb.z, qb.w}; o.ov[2 * pr] = (v2u){qo.x, qo.y}; o.ov[2 * pr + 1] = (v2u){qo.z, qo.w}; }
;         o.bv[4] = ldun<v2u>(bB + 2048, L.o8); o.ov[4] = ldun<v2u>(bO + 2048, L.o8);
;         o.wi = ldu<f32x4>(upin((const char*)F.WI + (size_t)ud * 256), L.wi);
;     }
;     ...
;     const float gl = ((const LAS float*)(St + 4 * 80 * 72))[(dir ? (s < 4 ? 3 - s : 39 - s) : s) * 2 + dir];
;     f32x4 O[NT];
; #pragma unroll
;     for (int t = 0; t < NT; ++t) {
;         const LAS bf16_t* sp2 = Sb + (16 * t + lr) * 72 + 8 * lq;
;         const bf16x8 s0 = *(const LAS bf16x8*)sp2, s1 = *(const LAS bf16x8*)(sp2 + 32);
;         const f32x4 bv = unpack4(use.bv[t]), ov = unpack4(use.ov[t]);
;         if (GDN) {
;             f32x4 o = ov, sn = S[t] * gl + bv;
.LBB0_361:
	s_min_u32 s1, s25, 33
	s_add_i32 s1, s1, 2
	s_and_b64 s[4:5], exec, s[10:11]
	s_cselect_b32 s3, 3, 39
	s_sub_i32 s3, s3, s1
	s_and_b64 s[4:5], s[90:91], exec
	s_cselect_b32 s1, s1, s3
	s_lshl_b32 s3, s1, 6
	s_cmp_lt_i32 s1, 4
	s_cselect_b32 s4, s63, s33
	s_add_i32 s3, s4, s3
	s_mul_i32 s6, s3, 0xd00
	s_add_i32 s1, s1, s31
	s_ashr_i32 s7, s6, 31
	s_lshl_b32 s1, s1, 1
	s_or_b64 s[6:7], s[36:37], s[6:7]
	s_add_i32 s4, s1, s68
	s_lshl_b64 s[6:7], s[6:7], 1
	s_add_u32 s6, s16, s6
	s_addc_u32 s7, s17, s7
	global_load_dwordx4 v[56:59], v186, s[6:7]
	global_load_dwordx4 v[48:51], v186, s[6:7] offset:64
	s_ashr_i32 s5, s4, 31
	s_mul_i32 s3, s4, 0x5000
	v_readlane_b32 s6, v254, 46
	s_mul_hi_i32 s1, s4, 0x5000
	s_add_u32 s6, s6, s3
	v_readlane_b32 s3, v254, 47
	s_addc_u32 s7, s3, s1
	s_mov_b64 s[8:9], s[6:7]
	s_add_u32 s6, s6, 0x2800
	s_addc_u32 s7, s7, 0
	global_load_dwordx4 v[84:87], v185, s[6:7] nt
	global_load_dwordx4 v[88:91], v185, s[8:9] nt
	global_load_dwordx4 v[76:79], v185, s[6:7] offset:1024 nt
	global_load_dwordx4 v[80:83], v185, s[8:9] offset:1024 nt
	global_load_dwordx2 v[144:145], v184, s[6:7] offset:2048 nt
	global_load_dwordx2 v[2:3], v184, s[8:9] offset:2048 nt
	s_lshl_b64 s[4:5], s[4:5], 8
	v_readlane_b32 s6, v254, 52
	v_readlane_b32 s7, v254, 53
	s_add_u32 s4, s6, s4
	s_addc_u32 s5, s7, s5
	s_cmp_gt_u32 s25, 3
	s_cselect_b32 s1, 39, 3
	s_add_i32 s1, s1, s24
	s_add_i32 s1, s1, 3
	global_load_dwordx4 v[72:75], v0, s[4:5]
	s_and_b64 s[4:5], s[90:91], exec
	s_cselect_b32 s1, s25, s1
	s_lshl_b32 s1, s1, 3
	s_add_i32 s1, s34, s1
	v_mov_b32_e32 v0, s1
	v_add_u32_e32 v164, v201, v121
	ds_read_b32 v0, v0 offset:46080
	ds_read_b128 v[104:107], v164
	ds_read_b128 v[108:111], v164 offset:64
	ds_read_b128 v[212:215], v164 offset:2304
	ds_read_b128 v[216:219], v164 offset:2368
	ds_read_b128 v[224:227], v164 offset:4608
	ds_read_b128 v[242:245], v164 offset:4672
	s_waitcnt lgkmcnt(5)
	v_mfma_f32_16x16x32_bf16 v[104:107], v[40:43], v[104:107], 0
	v_lshlrev_b32_e32 v112, 16, v92
	v_and_b32_e32 v113, 0xffff0000, v92
	v_lshlrev_b32_e32 v92, 16, v93
	s_waitcnt lgkmcnt(4)
	v_mfma_f32_16x16x32_bf16 v[104:107], v[36:39], v[108:111], v[104:107]
	v_and_b32_e32 v93, 0xffff0000, v93
	v_lshlrev_b32_e32 v114, 16, v96
	v_and_b32_e32 v115, 0xffff0000, v96
	v_lshlrev_b32_e32 v96, 16, v97
	v_and_b32_e32 v97, 0xffff0000, v97
	v_pk_fma_f32 v[150:151], v[150:151], v[0:1], v[92:93] op_sel_hi:[1,0,1]
	s_nop 1
	v_pk_fma_f32 v[92:93], v[62:63], v[106:107], v[96:97]
	v_pk_fma_f32 v[96:97], v[60:61], v[104:105], v[114:115]
	s_waitcnt lgkmcnt(3)
	v_mfma_f32_16x16x32_bf16 v[104:107], v[40:43], v[212:215], 0
	v_fma_f32 v148, v148, v0, v112
	v_fma_f32 v149, v149, v0, v113
	v_lshlrev_b32_e32 v112, 16, v94
	v_and_b32_e32 v113, 0xffff0000, v94
	s_waitcnt lgkmcnt(2)
	v_mfma_f32_16x16x32_bf16 v[104:107], v[36:39], v[216:219], v[104:107]
	ds_read_b128 v[212:215], v164 offset:6912
	ds_read_b128 v[216:219], v164 offset:6976
	v_lshlrev_b32_e32 v94, 16, v95
	v_and_b32_e32 v95, 0xffff0000, v95
	v_lshlrev_b32_e32 v114, 16, v98
	v_and_b32_e32 v115, 0xffff0000, v98
	v_lshlrev_b32_e32 v98, 16, v99
	v_and_b32_e32 v99, 0xffff0000, v99
	v_pk_fma_f32 v[152:153], v[152:153], v[0:1], v[94:95] op_sel_hi:[1,0,1]
	s_nop 0
	v_pk_fma_f32 v[94:95], v[62:63], v[106:107], v[98:99]
	v_pk_fma_f32 v[98:99], v[60:61], v[104:105], v[114:115]
	s_waitcnt lgkmcnt(3)
	v_mfma_f32_16x16x32_bf16 v[104:107], v[40:43], v[224:227], 0
	v_fma_f32 v154, v154, v0, v112
	v_fma_f32 v155, v155, v0, v113
	v_lshlrev_b32_e32 v112, 16, v64
	v_and_b32_e32 v113, 0xffff0000, v64
	s_waitcnt lgkmcnt(2)
; template <int N> __device__ __forceinline__ float row16_bcast(float v) { return dppf<0x150 + N>(v); }
; __device__ __forceinline__ float frcp(float x) { return __builtin_amdgcn_rcpf(x); }
;     ...
;             o = __builtin_amdgcn_mfma_f32_16x16x32_bf16(use.Qf[0], s0, o, 0, 0, 0); o = __builtin_amdgcn_mfma_f32_16x16x32_bf16(use.Qf[1], s1, o, 0, 0, 0);
;             S[t] = S[t] * gl + bv; O[t] = o * use.wi + ov; }
;     }
;     if (!GDN) {
; #pragma unroll
;         for (int i = 0; i < 4; ++i) { const float den = row16_bcast<0>(O[NT - 1][i]), fl = row16_bcast<1>(O[NT - 1][i]); const float dv = frcp(fmaxf(fabsf(den), fl));
; #pragma unroll
;             for (int t = 0; t < 4; ++t) O[t][i] *= dv; }
;     }
; #pragma unroll
;     for (int t = 0; t < 4; ++t) Oprev[t] = O[t];
	v_mfma_f32_16x16x32_bf16 v[104:107], v[36:39], v[242:245], v[104:107]
	ds_read_b128 v[224:227], v164 offset:9216
	ds_read_b128 v[242:245], v164 offset:9280
	v_lshlrev_b32_e32 v114, 16, v68
	v_and_b32_e32 v115, 0xffff0000, v68
	v_lshlrev_b32_e32 v68, 16, v69
	v_and_b32_e32 v69, 0xffff0000, v69
	v_pk_fma_f32 v[158:159], v[158:159], v[0:1], v[112:113] op_sel_hi:[1,0,1]
	s_nop 2
	v_pk_fma_f32 v[116:117], v[62:63], v[106:107], v[68:69]
	v_pk_fma_f32 v[112:113], v[60:61], v[104:105], v[114:115]
	v_lshlrev_b32_e32 v64, 16, v65
	v_and_b32_e32 v65, 0xffff0000, v65
	v_pk_fma_f32 v[156:157], v[156:157], v[0:1], v[64:65] op_sel_hi:[1,0,1]
	v_lshlrev_b32_e32 v68, 16, v66
	v_and_b32_e32 v69, 0xffff0000, v66
	v_lshlrev_b32_e32 v114, 16, v67
	v_and_b32_e32 v115, 0xffff0000, v67
	s_waitcnt lgkmcnt(3)
	v_mfma_f32_16x16x32_bf16 v[64:67], v[40:43], v[212:215], 0
	v_lshlrev_b32_e32 v118, 16, v70
	v_and_b32_e32 v119, 0xffff0000, v70
	v_lshlrev_b32_e32 v70, 16, v71
	s_waitcnt lgkmcnt(2)
	v_mfma_f32_16x16x32_bf16 v[64:67], v[36:39], v[216:219], v[64:67]
	v_and_b32_e32 v71, 0xffff0000, v71
	v_pk_fma_f32 v[162:163], v[162:163], v[0:1], v[68:69] op_sel_hi:[1,0,1]
	v_lshlrev_b32_e32 v108, 16, v142
	v_and_b32_e32 v109, 0xffff0000, v142
	v_lshlrev_b32_e32 v104, 16, v146
	s_nop 2
	v_pk_fma_f32 v[166:167], v[62:63], v[66:67], v[70:71]
	v_pk_fma_f32 v[118:119], v[60:61], v[64:65], v[118:119]
	s_waitcnt lgkmcnt(1)
	v_mfma_f32_16x16x32_bf16 v[40:43], v[40:43], v[224:227], 0
	v_and_b32_e32 v105, 0xffff0000, v146
	v_lshlrev_b32_e32 v106, 16, v147
	v_and_b32_e32 v107, 0xffff0000, v147
	s_waitcnt lgkmcnt(0)
	v_mfma_f32_16x16x32_bf16 v[36:39], v[36:39], v[242:245], v[40:43]
	v_fma_f32 v160, v160, v0, v114
	v_fma_f32 v161, v161, v0, v115
	v_pk_fma_f32 v[178:179], v[182:183], v[0:1], v[106:107] op_sel_hi:[1,0,1]
	v_pk_fma_f32 v[164:165], v[180:181], v[0:1], v[104:105] op_sel_hi:[1,0,1]
	v_lshlrev_b32_e32 v110, 16, v143
	v_and_b32_e32 v111, 0xffff0000, v143
	s_nop 1
	v_pk_fma_f32 v[36:37], v[60:61], v[36:37], v[108:109]
	v_pk_fma_f32 v[38:39], v[62:63], v[38:39], v[110:111]
	s_nop 0
	v_mov_b32_dpp v0, v36 row_newbcast:0 row_mask:0xf bank_mask:0xf bound_ctrl:1
	v_mov_b32_dpp v36, v36 row_newbcast:1 row_mask:0xf bank_mask:0xf bound_ctrl:1
	v_max_f32_e32 v36, v36, v36
	v_max_f32_e64 v0, |v0|, |v0|
	v_max_f32_e32 v0, v0, v36
	v_rcp_f32_e32 v36, v0
	s_nop 0
	v_mov_b32_dpp v0, v37 row_newbcast:0 row_mask:0xf bank_mask:0xf bound_ctrl:1
	v_mov_b32_dpp v37, v37 row_newbcast:1 row_mask:0xf bank_mask:0xf bound_ctrl:1
	v_max_f32_e32 v37, v37, v37
	v_max_f32_e64 v0, |v0|, |v0|
	v_max_f32_e32 v0, v0, v37
	v_rcp_f32_e32 v37, v0
	s_nop 0
	v_mov_b32_dpp v0, v38 row_newbcast:0 row_mask:0xf bank_mask:0xf bound_ctrl:1
	v_mov_b32_dpp v38, v38 row_newbcast:1 row_mask:0xf bank_mask:0xf bound_ctrl:1
	v_max_f32_e32 v38, v38, v38
	v_max_f32_e64 v0, |v0|, |v0|
	v_max_f32_e32 v0, v0, v38
	v_rcp_f32_e32 v38, v0
	v_pk_mul_f32 v[104:105], v[96:97], v[36:37]
	v_mov_b32_dpp v0, v39 row_newbcast:0 row_mask:0xf bank_mask:0xf bound_ctrl:1
	v_mov_b32_dpp v39, v39 row_newbcast:1 row_mask:0xf bank_mask:0xf bound_ctrl:1
	v_max_f32_e32 v39, v39, v39
	v_max_f32_e64 v0, |v0|, |v0|
	v_max_f32_e32 v0, v0, v39
	v_rcp_f32_e32 v39, v0
	v_pk_mul_f32 v[108:109], v[98:99], v[36:37]
	v_pk_mul_f32 v[112:113], v[112:113], v[36:37]
	v_pk_mul_f32 v[106:107], v[92:93], v[38:39]
	v_pk_mul_f32 v[110:111], v[94:95], v[38:39]
	v_pk_mul_f32 v[114:115], v[116:117], v[38:39]
	v_pk_mul_f32 v[116:117], v[118:119], v[36:37]
	v_pk_mul_f32 v[118:119], v[166:167], v[38:39]

; #define LAS __attribute__((address_space(3)))
; template <bool GDN, int NT> __device__ __forceinline__ void scan_load(const Frame& F, int b, int h, int dir, const ScanLane& L, int s, ScanOps<NT>& o) {
;     const int cidx = dir ? (s < 4 ? 3 - s : 39 - s) : s;
;     const int ud = ((b * 4 + h) * 36 + cidx) * 2 + dir;
;     if (GDN) {
;         const char* base = (const char*)F.PG + (size_t)ud * 32768;
;         const char* bM = upin(base); const char* bB = upin(base + 8192); const char* bQ = upin(base + 16384); const char* bO = upin(base + 24576);
; #pragma unroll
;         for (int ks = 0; ks < 2; ++ks) { o.Mf[ks] = ldun<bf16x8>(bM + ks * 1024, L.o16); o.Qf[ks] = ldun<bf16x8>(bQ + ks * 1024, L.o16); }
; #pragma unroll
;         for (int pr = 0; pr < 2; ++pr) { const v4u qb = ldun<v4u>(bB + pr * 1024, L.o16p), qo = ldun<v4u>(bO + pr * 1024, L.o16p);
;             o.bv[2 * pr] = (v2u){qb.x, qb.y}; o.bv[2 * pr + 1] = (v2u){qb.z, qb.w}; o.ov[2 * pr] = (v2u){qo.x, qo.y}; o.ov[2 * pr + 1] = (v2u){qo.z, qo.w}; }
;         o.wi = (f32x4){1.f, 1.f, 1.f, 1.f};
;     } else {
;         const char* zq = upin((const char*)F.Z + ((size_t)chunk_row0(b, cidx) * ZW + ZC_LQ + h * 64) * 2);
; #pragma unroll
;         for (int ks = 0; ks < 2; ++ks) { o.Qf[ks] = ldu<bf16x8>(zq + ks * 64, L.zq); o.Mf[ks] = o.Qf[ks]; }
;         const char* base = (const char*)F.PM + (size_t)ud * 20480;
;         const char* bO = upin(base); const char* bB = upin(base + 10240);
; #pragma unroll
;         for (int pr = 0; pr < 2; ++pr) { const v4u qb = ldun<v4u>(bB + pr * 1024, L.o16p), qo = ldun<v4u>(bO + pr * 1024, L.o16p);
;             o.bv[2 * pr] = (v2u){qb.x, qb.y}; o.bv[2 * pr + 1] = (v2u){qb.z, qb.w}; o.ov[2 * pr] = (v2u){qo.x, qo.y}; o.ov[2 * pr + 1] = (v2u){qo.z, qo.w}; }
;         o.bv[4] = ldun<v2u>(bB + 2048, L.o8); o.ov[4] = ldun<v2u>(bO + 2048, L.o8);
;         o.wi = ldu<f32x4>(upin((const char*)F.WI + (size_t)ud * 256), L.wi);
;     }
;     ...
;     if (s < 36) {
; #pragma unroll
;         for (int t = 0; t < NT; ++t) *(LAS v2u*)(Sb + (16 * t + lr) * 72 + 16 * wq + 4 * lq) = pack4(S[t]); }
;     if (s == 21 || s == 3) asm volatile("s_waitcnt vmcnt(0)" ::: "memory");
;     else if (scan_needfin(s - 1)) { if (GDN) asm volatile("s_waitcnt vmcnt(14)" ::: "memory"); else asm volatile("s_waitcnt vmcnt(15)" ::: "memory"); }
.LBB0_396:
	s_min_u32 s1, s4, 33
	s_add_i32 s8, s1, 2
	s_and_b64 s[6:7], exec, s[10:11]
	s_cselect_b32 s1, 3, 39
	s_sub_i32 s9, s1, s8
	s_and_b64 s[6:7], s[90:91], exec
	s_cselect_b32 s6, s8, s9
	s_lshl_b32 s7, s6, 6
	s_cmp_lt_i32 s6, 4
	s_cselect_b32 s8, s63, s33
	s_add_i32 s7, s8, s7
	s_mul_i32 s8, s7, 0xd00
	s_add_i32 s6, s6, s31
	s_ashr_i32 s9, s8, 31
	s_lshl_b32 s6, s6, 1
	s_or_b64 s[8:9], s[36:37], s[8:9]
	s_add_i32 s6, s6, s68
	s_lshl_b64 s[8:9], s[8:9], 1
	s_add_u32 s8, s16, s8
	s_addc_u32 s9, s17, s9
	global_load_dwordx4 v[40:43], v36, s[8:9]
	s_nop 0
	global_load_dwordx4 v[36:39], v36, s[8:9] offset:64
	s_ashr_i32 s7, s6, 31
	s_mul_i32 s8, s6, 0x5000
	v_readlane_b32 s10, v254, 46
	s_mul_hi_i32 s9, s6, 0x5000
	s_add_u32 s8, s10, s8
	v_readlane_b32 s10, v254, 47
	s_addc_u32 s9, s10, s9
	s_mov_b64 s[10:11], s[8:9]
	s_add_u32 s8, s8, 0x2800
	s_addc_u32 s9, s9, 0
	global_load_dwordx4 v[92:95], v60, s[8:9] nt
	global_load_dwordx4 v[64:67], v60, s[8:9] offset:1024 nt
	global_load_dwordx4 v[96:99], v60, s[10:11] nt
	global_load_dwordx4 v[68:71], v60, s[10:11] offset:1024 nt
	global_load_dwordx2 v[146:147], v61, s[8:9] offset:2048 nt
	global_load_dwordx2 v[142:143], v61, s[10:11] offset:2048 nt
	s_lshl_b64 s[6:7], s[6:7], 8
	v_readlane_b32 s8, v254, 52
	v_readlane_b32 s9, v254, 53
	s_add_u32 s6, s8, s6
	s_addc_u32 s7, s9, s7
	global_load_dwordx4 v[60:63], v0, s[6:7]
	s_add_i32 s5, s5, 2
	s_and_b64 s[6:7], s[90:91], exec
	s_cselect_b32 s5, s4, s5
	s_lshl_b32 s6, s5, 3
	s_add_i32 s6, s34, s6
	v_mov_b32_e32 v0, s6
	v_add_u32_e32 v203, v201, v121
	ds_read_b128 v[104:107], v203 offset:11520
	ds_read_b32 v0, v0 offset:46080
	ds_read_b128 v[108:111], v203 offset:11584
	ds_read_b128 v[212:215], v203 offset:13824
	ds_read_b128 v[216:219], v203 offset:13888
	ds_read_b128 v[224:227], v203 offset:16128
	ds_read_b128 v[242:245], v203 offset:18432
	s_waitcnt lgkmcnt(6)
	v_mfma_f32_16x16x32_bf16 v[104:107], v[24:27], v[104:107], 0
	s_waitcnt vmcnt(63)
	v_lshlrev_b32_e32 v116, 16, v44
	v_and_b32_e32 v117, 0xffff0000, v44
	v_lshlrev_b32_e32 v118, 16, v45
	v_and_b32_e32 v119, 0xffff0000, v45
	s_waitcnt lgkmcnt(4)
	v_mfma_f32_16x16x32_bf16 v[104:107], v[20:23], v[108:111], v[104:107]
	v_pk_fma_f32 v[180:181], v[150:151], v[0:1], v[118:119] op_sel_hi:[1,0,1]
	v_pk_fma_f32 v[182:183], v[148:149], v[0:1], v[116:117] op_sel_hi:[1,0,1]
	s_waitcnt lgkmcnt(3)
	v_mfma_f32_16x16x32_bf16 v[112:115], v[24:27], v[212:215], 0
	v_lshlrev_b32_e32 v148, 16, v46
	s_waitcnt lgkmcnt(2)
	v_mfma_f32_16x16x32_bf16 v[108:111], v[20:23], v[216:219], v[112:115]
	ds_read_b128 v[212:215], v203 offset:16192
	ds_read_b128 v[216:219], v203 offset:18496
	v_and_b32_e32 v149, 0xffff0000, v46
	v_lshlrev_b32_e32 v150, 16, v47
	v_and_b32_e32 v151, 0xffff0000, v47
	s_waitcnt lgkmcnt(3)
	v_mfma_f32_16x16x32_bf16 v[116:119], v[24:27], v[224:227], 0
	v_fma_f32 v150, v152, v0, v150
	v_fma_f32 v151, v153, v0, v151
	v_pk_fma_f32 v[154:155], v[154:155], v[0:1], v[148:149] op_sel_hi:[1,0,1]
	s_waitcnt vmcnt(63)
	v_lshlrev_b32_e32 v152, 16, v28
	v_and_b32_e32 v153, 0xffff0000, v28
	v_lshlrev_b32_e32 v148, 16, v29
	v_and_b32_e32 v149, 0xffff0000, v29
	s_waitcnt lgkmcnt(1)
	v_mfma_f32_16x16x32_bf16 v[112:115], v[20:23], v[212:215], v[116:119]
	v_fma_f32 v148, v156, v0, v148
	v_fma_f32 v149, v157, v0, v149
	v_pk_fma_f32 v[152:153], v[158:159], v[0:1], v[152:153] op_sel_hi:[1,0,1]
	v_lshlrev_b32_e32 v170, 16, v30
	v_mfma_f32_16x16x32_bf16 v[156:159], v[24:27], v[242:245], 0
	ds_read_b128 v[224:227], v203 offset:20736
	ds_read_b128 v[242:245], v203 offset:20800
	v_and_b32_e32 v171, 0xffff0000, v30
	v_lshlrev_b32_e32 v172, 16, v31
	s_waitcnt lgkmcnt(2)
	v_mfma_f32_16x16x32_bf16 v[116:119], v[20:23], v[216:219], v[156:159]
	v_and_b32_e32 v173, 0xffff0000, v31
	v_pk_fma_f32 v[184:185], v[160:161], v[0:1], v[172:173] op_sel_hi:[1,0,1]
	v_pk_fma_f32 v[160:161], v[162:163], v[0:1], v[170:171] op_sel_hi:[1,0,1]
	s_waitcnt lgkmcnt(1)
	v_mfma_f32_16x16x32_bf16 v[166:169], v[24:27], v[224:227], 0
	s_waitcnt vmcnt(63)
	v_lshlrev_b32_e32 v162, 16, v140
	v_and_b32_e32 v163, 0xffff0000, v140
	s_waitcnt vmcnt(63)
	v_lshlrev_b32_e32 v172, 16, v138
	s_waitcnt lgkmcnt(0)
	v_mfma_f32_16x16x32_bf16 v[166:169], v[20:23], v[242:245], v[166:169]
	v_and_b32_e32 v173, 0xffff0000, v138
	v_lshlrev_b32_e32 v174, 16, v139
	v_and_b32_e32 v175, 0xffff0000, v139
	v_lshlrev_b32_e32 v170, 16, v141
	v_and_b32_e32 v171, 0xffff0000, v141
	v_pk_fma_f32 v[158:159], v[164:165], v[0:1], v[162:163] op_sel_hi:[1,0,1]
	s_waitcnt vmcnt(63)
	s_nop 0
	v_pk_fma_f32 v[168:169], v[102:103], v[168:169], v[174:175]
	v_pk_fma_f32 v[162:163], v[100:101], v[166:167], v[172:173]
	v_pk_fma_f32 v[156:157], v[178:179], v[0:1], v[170:171] op_sel_hi:[1,0,1]
	v_mov_b32_dpp v165, v168 row_newbcast:0 row_mask:0xf bank_mask:0xf bound_ctrl:1
	v_mov_b32_dpp v187, v162 row_newbcast:0 row_mask:0xf bank_mask:0xf bound_ctrl:1
	v_mov_b32_dpp v193, v162 row_newbcast:1 row_mask:0xf bank_mask:0xf bound_ctrl:1
	v_mov_b32_dpp v179, v163 row_newbcast:0 row_mask:0xf bank_mask:0xf bound_ctrl:1
	v_mov_b32_dpp v186, v163 row_newbcast:1 row_mask:0xf bank_mask:0xf bound_ctrl:1
	v_mov_b32_dpp v178, v168 row_newbcast:1 row_mask:0xf bank_mask:0xf bound_ctrl:1
	v_mov_b32_dpp v163, v169 row_newbcast:0 row_mask:0xf bank_mask:0xf bound_ctrl:1
	v_mov_b32_dpp v164, v169 row_newbcast:1 row_mask:0xf bank_mask:0xf bound_ctrl:1
	v_mov_b32_e32 v0, v120
	v_mov_b32_e32 v191, v197
	v_mov_b32_e32 v188, v194
	v_mov_b32_e32 v190, v196
	v_mov_b32_e32 v192, v199
	v_mov_b32_e32 v166, v198
	v_mov_b32_e32 v162, v200
	v_mov_b32_e32 v189, v195
	s_cmp_gt_u32 s25, 33
	s_cbranch_scc1 .LBB0_398
	v_cvt_pk_bf16_f32 v166, v182, v183
	v_cvt_pk_bf16_f32 v167, v180, v181
	ds_write_b64 v202, v[166:167]
	v_cvt_pk_bf16_f32 v166, v154, v155
	v_cvt_pk_bf16_f32 v167, v150, v151
	ds_write_b64 v202, v[166:167] offset:2304
	v_cvt_pk_bf16_f32 v166, v152, v153
	v_cvt_pk_bf16_f32 v167, v148, v149
	ds_write_b64 v202, v[166:167] offset:4608
	v_cvt_pk_bf16_f32 v166, v160, v161
	v_cvt_pk_bf16_f32 v167, v184, v185
	ds_write_b64 v202, v[166:167] offset:6912
	v_cvt_pk_bf16_f32 v166, v158, v159
	v_cvt_pk_bf16_f32 v167, v156, v157
	ds_write_b64 v202, v[166:167] offset:9216

; template <bool GDN, int NT> __device__ __forceinline__ void scan_load(const Frame& F, int b, int h, int dir, const ScanLane& L, int s, ScanOps<NT>& o) {
;     const int cidx = dir ? (s < 4 ? 3 - s : 39 - s) : s;
;     const int ud = ((b * 4 + h) * 36 + cidx) * 2 + dir;
;     if (GDN) {
;         const char* base = (const char*)F.PG + (size_t)ud * 32768;
;         const char* bM = upin(base); const char* bB = upin(base + 8192); const char* bQ = upin(base + 16384); const char* bO = upin(base + 24576);
; #pragma unroll
;         for (int ks = 0; ks < 2; ++ks) { o.Mf[ks] = ldun<bf16x8>(bM + ks * 1024, L.o16); o.Qf[ks] = ldun<bf16x8>(bQ + ks * 1024, L.o16); }
; #pragma unroll
;         for (int pr = 0; pr < 2; ++pr) { const v4u qb = ldun<v4u>(bB + pr * 1024, L.o16p), qo = ldun<v4u>(bO + pr * 1024, L.o16p);
;             o.bv[2 * pr] = (v2u){qb.x, qb.y}; o.bv[2 * pr + 1] = (v2u){qb.z, qb.w}; o.ov[2 * pr] = (v2u){qo.x, qo.y}; o.ov[2 * pr + 1] = (v2u){qo.z, qo.w}; }
;         o.wi = (f32x4){1.f, 1.f, 1.f, 1.f};
;     } else {
;         const char* zq = upin((const char*)F.Z + ((size_t)chunk_row0(b, cidx) * ZW + ZC_LQ + h * 64) * 2);
; #pragma unroll
;         for (int ks = 0; ks < 2; ++ks) { o.Qf[ks] = ldu<bf16x8>(zq + ks * 64, L.zq); o.Mf[ks] = o.Qf[ks]; }
;         const char* base = (const char*)F.PM + (size_t)ud * 20480;
;         const char* bO = upin(base); const char* bB = upin(base + 10240);
; #pragma unroll
;         for (int pr = 0; pr < 2; ++pr) { const v4u qb = ldun<v4u>(bB + pr * 1024, L.o16p), qo = ldun<v4u>(bO + pr * 1024, L.o16p);
;             o.bv[2 * pr] = (v2u){qb.x, qb.y}; o.bv[2 * pr + 1] = (v2u){qb.z, qb.w}; o.ov[2 * pr] = (v2u){qo.x, qo.y}; o.ov[2 * pr + 1] = (v2u){qo.z, qo.w}; }
;         o.bv[4] = ldun<v2u>(bB + 2048, L.o8); o.ov[4] = ldun<v2u>(bO + 2048, L.o8);
;         o.wi = ldu<f32x4>(upin((const char*)F.WI + (size_t)ud * 256), L.wi);
;     }
;     ...
;     const float gl = ((const LAS float*)(St + 4 * 80 * 72))[(dir ? (s < 4 ? 3 - s : 39 - s) : s) * 2 + dir];
;     f32x4 O[NT];
; #pragma unroll
;     for (int t = 0; t < NT; ++t) {
;         const LAS bf16_t* sp2 = Sb + (16 * t + lr) * 72 + 8 * lq;
;         const bf16x8 s0 = *(const LAS bf16x8*)sp2, s1 = *(const LAS bf16x8*)(sp2 + 32);
;         const f32x4 bv = unpack4(use.bv[t]), ov = unpack4(use.ov[t]);
;         if (GDN) {
;             f32x4 o = ov, sn = S[t] * gl + bv;
.LBB0_409:
	s_min_u32 s5, s3, 33
	s_add_i32 s8, s5, 2
	s_sub_i32 s5, 37, s5
	s_and_b64 s[6:7], s[90:91], exec
	s_cselect_b32 s5, s8, s5
	s_lshl_b32 s6, s5, 6
	s_add_i32 s6, s6, s33
	s_add_i32 s5, s5, s31
	s_mulk_i32 s6, 0xd00
	s_lshl_b32 s5, s5, 1
	s_or_b32 s6, s36, s6
	s_mov_b32 s7, s37
	s_add_i32 s92, s5, s68
	s_lshl_b64 s[6:7], s[6:7], 1
	s_add_u32 s6, s16, s6
	s_addc_u32 s7, s17, s7
	global_load_dwordx4 v[24:27], v190, s[6:7]
	global_load_dwordx4 v[20:23], v190, s[6:7] offset:64
	s_mul_i32 s6, s92, 0x5000
	v_readlane_b32 s7, v254, 46
	s_mul_hi_u32 s5, s92, 0x5000
	s_add_u32 s6, s7, s6
	v_readlane_b32 s7, v254, 47
	s_addc_u32 s7, s7, s5
	s_mov_b64 s[8:9], s[6:7]
	s_add_u32 s6, s6, 0x2800
	s_addc_u32 s7, s7, 0
	s_nop 0
	global_load_dwordx4 v[44:47], v189, s[6:7] nt
	global_load_dwordx4 v[28:31], v189, s[6:7] offset:1024 nt
	global_load_dwordx4 v[52:55], v189, s[8:9] nt
	global_load_dwordx4 v[32:35], v189, s[8:9] offset:1024 nt
	global_load_dwordx2 v[140:141], v188, s[6:7] offset:2048 nt
	global_load_dwordx2 v[138:139], v188, s[8:9] offset:2048 nt
	s_lshl_b64 s[6:7], s[92:93], 8
	v_readlane_b32 s8, v254, 52
	v_readlane_b32 s9, v254, 53
	s_add_u32 s6, s8, s6
	s_addc_u32 s7, s9, s7
	global_load_dwordx4 v[100:103], v0, s[6:7]
	s_add_i32 s6, s4, 1
	s_and_b64 s[4:5], s[90:91], exec
	s_cselect_b32 s4, s3, s6
	s_lshl_b32 s4, s4, 3
	s_add_i32 s4, s34, s4
	v_mov_b32_e32 v0, s4
	ds_read_b32 v0, v0 offset:46080
	ds_read_b128 v[204:207], v203
	ds_read_b128 v[208:211], v203 offset:64
	ds_read_b128 v[212:215], v203 offset:2304
	ds_read_b128 v[216:219], v203 offset:2368
	ds_read_b128 v[224:227], v203 offset:4608
	ds_read_b128 v[242:245], v203 offset:4672
	s_waitcnt lgkmcnt(5)
	v_mfma_f32_16x16x32_bf16 v[204:207], v[56:59], v[204:207], 0
	v_lshlrev_b32_e32 v112, 16, v84
	v_and_b32_e32 v113, 0xffff0000, v84
	v_lshlrev_b32_e32 v84, 16, v85
	s_waitcnt lgkmcnt(4)
	v_mfma_f32_16x16x32_bf16 v[204:207], v[48:51], v[208:211], v[204:207]
	v_and_b32_e32 v85, 0xffff0000, v85
	v_lshlrev_b32_e32 v114, 16, v88
	v_and_b32_e32 v115, 0xffff0000, v88
	v_lshlrev_b32_e32 v88, 16, v89
	v_and_b32_e32 v89, 0xffff0000, v89
	v_pk_fma_f32 v[180:181], v[180:181], v[0:1], v[84:85] op_sel_hi:[1,0,1]
	s_nop 1
	v_pk_fma_f32 v[84:85], v[72:73], v[204:205], v[114:115]
	v_pk_fma_f32 v[88:89], v[74:75], v[206:207], v[88:89]
	s_waitcnt lgkmcnt(3)
	v_mfma_f32_16x16x32_bf16 v[204:207], v[56:59], v[212:215], 0
	v_fma_f32 v182, v182, v0, v112
	v_fma_f32 v183, v183, v0, v113
	v_lshlrev_b32_e32 v112, 16, v86
	v_and_b32_e32 v113, 0xffff0000, v86
	s_waitcnt lgkmcnt(2)
	v_mfma_f32_16x16x32_bf16 v[204:207], v[48:51], v[216:219], v[204:207]
	ds_read_b128 v[212:215], v203 offset:6912
	ds_read_b128 v[216:219], v203 offset:6976
	v_lshlrev_b32_e32 v86, 16, v87
	v_and_b32_e32 v87, 0xffff0000, v87
	v_lshlrev_b32_e32 v114, 16, v90
	v_and_b32_e32 v115, 0xffff0000, v90
	v_lshlrev_b32_e32 v90, 16, v91
	v_and_b32_e32 v91, 0xffff0000, v91
	v_pk_fma_f32 v[150:151], v[150:151], v[0:1], v[86:87] op_sel_hi:[1,0,1]
	s_nop 0
	v_pk_fma_f32 v[86:87], v[72:73], v[204:205], v[114:115]
	v_pk_fma_f32 v[90:91], v[74:75], v[206:207], v[90:91]
	s_waitcnt lgkmcnt(3)
	v_mfma_f32_16x16x32_bf16 v[204:207], v[56:59], v[224:227], 0
	v_fma_f32 v154, v154, v0, v112
	v_fma_f32 v155, v155, v0, v113
	v_lshlrev_b32_e32 v112, 16, v76
	v_and_b32_e32 v113, 0xffff0000, v76
	s_waitcnt lgkmcnt(2)
	v_mfma_f32_16x16x32_bf16 v[204:207], v[48:51], v[242:245], v[204:207]
	ds_read_b128 v[224:227], v203 offset:9216
	ds_read_b128 v[242:245], v203 offset:9280
	v_lshlrev_b32_e32 v76, 16, v77
	v_and_b32_e32 v77, 0xffff0000, v77
	v_lshlrev_b32_e32 v114, 16, v80
	v_and_b32_e32 v115, 0xffff0000, v80
	v_lshlrev_b32_e32 v80, 16, v81
	v_and_b32_e32 v81, 0xffff0000, v81
	v_pk_fma_f32 v[148:149], v[148:149], v[0:1], v[76:77] op_sel_hi:[1,0,1]
	s_nop 0
	v_pk_fma_f32 v[76:77], v[72:73], v[204:205], v[114:115]
	v_pk_fma_f32 v[80:81], v[74:75], v[206:207], v[80:81]
	s_waitcnt lgkmcnt(3)
	v_mfma_f32_16x16x32_bf16 v[204:207], v[56:59], v[212:215], 0
	v_fma_f32 v152, v152, v0, v112
	v_fma_f32 v153, v153, v0, v113
	v_lshlrev_b32_e32 v112, 16, v78
	v_and_b32_e32 v113, 0xffff0000, v78
	s_waitcnt lgkmcnt(2)
	v_mfma_f32_16x16x32_bf16 v[204:207], v[48:51], v[216:219], v[204:207]
	v_lshlrev_b32_e32 v78, 16, v79
	v_and_b32_e32 v79, 0xffff0000, v79
	v_lshlrev_b32_e32 v114, 16, v82
	v_and_b32_e32 v115, 0xffff0000, v82
	v_lshlrev_b32_e32 v82, 16, v83
	v_and_b32_e32 v83, 0xffff0000, v83
	v_pk_fma_f32 v[184:185], v[184:185], v[0:1], v[78:79] op_sel_hi:[1,0,1]
	s_nop 0
	v_pk_fma_f32 v[78:79], v[72:73], v[204:205], v[114:115]
	v_pk_fma_f32 v[82:83], v[74:75], v[206:207], v[82:83]
	s_waitcnt lgkmcnt(1)
	v_mfma_f32_16x16x32_bf16 v[204:207], v[56:59], v[224:227], 0
	v_lshlrev_b32_e32 v116, 16, v2
	v_and_b32_e32 v117, 0xffff0000, v2
	v_lshlrev_b32_e32 v2, 16, v3
	s_waitcnt lgkmcnt(0)
	v_mfma_f32_16x16x32_bf16 v[204:207], v[48:51], v[242:245], v[204:207]
	v_and_b32_e32 v3, 0xffff0000, v3
	v_pk_fma_f32 v[160:161], v[160:161], v[0:1], v[112:113] op_sel_hi:[1,0,1]
	v_lshlrev_b32_e32 v112, 16, v144
	v_and_b32_e32 v113, 0xffff0000, v144
	v_lshlrev_b32_e32 v114, 16, v145
	s_nop 2
	v_pk_fma_f32 v[204:205], v[72:73], v[204:205], v[116:117]
	v_pk_fma_f32 v[2:3], v[74:75], v[206:207], v[2:3]
	v_and_b32_e32 v115, 0xffff0000, v145
	v_mov_b32_dpp v206, v204 row_newbcast:0 row_mask:0xf bank_mask:0xf bound_ctrl:1
	v_mov_b32_dpp v204, v204 row_newbcast:1 row_mask:0xf bank_mask:0xf bound_ctrl:1
	v_max_f32_e32 v204, v204, v204
	v_max_f32_e64 v206, |v206|, |v206|
	v_max_f32_e32 v204, v206, v204
	v_rcp_f32_e32 v204, v204
	v_mov_b32_dpp v206, v205 row_newbcast:0 row_mask:0xf bank_mask:0xf bound_ctrl:1
	v_mov_b32_dpp v205, v205 row_newbcast:1 row_mask:0xf bank_mask:0xf bound_ctrl:1
	v_max_f32_e32 v205, v205, v205
	v_max_f32_e64 v206, |v206|, |v206|
	v_max_f32_e32 v205, v206, v205
	v_rcp_f32_e32 v205, v205
	v_mov_b32_dpp v206, v2 row_newbcast:0 row_mask:0xf bank_mask:0xf bound_ctrl:1
	v_mov_b32_dpp v2, v2 row_newbcast:1 row_mask:0xf bank_mask:0xf bound_ctrl:1
	v_max_f32_e32 v2, v2, v2
	v_max_f32_e64 v206, |v206|, |v206|
	v_max_f32_e32 v2, v206, v2
	v_rcp_f32_e32 v206, v2
	v_pk_fma_f32 v[156:157], v[156:157], v[0:1], v[114:115] op_sel_hi:[1,0,1]
	v_mov_b32_dpp v2, v3 row_newbcast:0 row_mask:0xf bank_mask:0xf bound_ctrl:1
	v_mov_b32_dpp v3, v3 row_newbcast:1 row_mask:0xf bank_mask:0xf bound_ctrl:1
	v_max_f32_e32 v3, v3, v3
	v_max_f32_e64 v2, |v2|, |v2|
	v_max_f32_e32 v2, v2, v3
	v_rcp_f32_e32 v207, v2
	v_pk_fma_f32 v[158:159], v[158:159], v[0:1], v[112:113] op_sel_hi:[1,0,1]
	v_pk_mul_f32 v[50:51], v[84:85], v[204:205]
	v_pk_mul_f32 v[112:113], v[86:87], v[204:205]
	v_pk_mul_f32 v[2:3], v[88:89], v[206:207]
	v_pk_mul_f32 v[118:119], v[90:91], v[206:207]
	v_pk_mul_f32 v[48:49], v[80:81], v[206:207]
	v_pk_mul_f32 v[56:57], v[76:77], v[204:205]
	v_pk_mul_f32 v[116:117], v[82:83], v[206:207]
	v_pk_mul_f32 v[114:115], v[78:79], v[204:205]
	s_branch .LBB0_413

; #define LAS __attribute__((address_space(3)))
; template <bool GDN, int NT> __device__ __forceinline__ void scan_load(const Frame& F, int b, int h, int dir, const ScanLane& L, int s, ScanOps<NT>& o) {
;     const int cidx = dir ? (s < 4 ? 3 - s : 39 - s) : s;
;     const int ud = ((b * 4 + h) * 36 + cidx) * 2 + dir;
;     if (GDN) {
;         const char* base = (const char*)F.PG + (size_t)ud * 32768;
;         const char* bM = upin(base); const char* bB = upin(base + 8192); const char* bQ = upin(base + 16384); const char* bO = upin(base + 24576);
; #pragma unroll
;         for (int ks = 0; ks < 2; ++ks) { o.Mf[ks] = ldun<bf16x8>(bM + ks * 1024, L.o16); o.Qf[ks] = ldun<bf16x8>(bQ + ks * 1024, L.o16); }
; #pragma unroll
;         for (int pr = 0; pr < 2; ++pr) { const v4u qb = ldun<v4u>(bB + pr * 1024, L.o16p), qo = ldun<v4u>(bO + pr * 1024, L.o16p);
;             o.bv[2 * pr] = (v2u){qb.x, qb.y}; o.bv[2 * pr + 1] = (v2u){qb.z, qb.w}; o.ov[2 * pr] = (v2u){qo.x, qo.y}; o.ov[2 * pr + 1] = (v2u){qo.z, qo.w}; }
;         o.wi = (f32x4){1.f, 1.f, 1.f, 1.f};
;     } else {
;         const char* zq = upin((const char*)F.Z + ((size_t)chunk_row0(b, cidx) * ZW + ZC_LQ + h * 64) * 2);
; #pragma unroll
;         for (int ks = 0; ks < 2; ++ks) { o.Qf[ks] = ldu<bf16x8>(zq + ks * 64, L.zq); o.Mf[ks] = o.Qf[ks]; }
;         const char* base = (const char*)F.PM + (size_t)ud * 20480;
;         const char* bO = upin(base); const char* bB = upin(base + 10240);
; #pragma unroll
;         for (int pr = 0; pr < 2; ++pr) { const v4u qb = ldun<v4u>(bB + pr * 1024, L.o16p), qo = ldun<v4u>(bO + pr * 1024, L.o16p);
;             o.bv[2 * pr] = (v2u){qb.x, qb.y}; o.bv[2 * pr + 1] = (v2u){qb.z, qb.w}; o.ov[2 * pr] = (v2u){qo.x, qo.y}; o.ov[2 * pr + 1] = (v2u){qo.z, qo.w}; }
;         o.bv[4] = ldun<v2u>(bB + 2048, L.o8); o.ov[4] = ldun<v2u>(bO + 2048, L.o8);
;         o.wi = ldu<f32x4>(upin((const char*)F.WI + (size_t)ud * 256), L.wi);
;     }
;     ...
;     if (s < 36) {
; #pragma unroll
;         for (int t = 0; t < NT; ++t) *(LAS v2u*)(Sb + (16 * t + lr) * 72 + 16 * wq + 4 * lq) = pack4(S[t]); }
;     if (s == 21 || s == 3) asm volatile("s_waitcnt vmcnt(0)" ::: "memory");
;     else if (scan_needfin(s - 1)) { if (GDN) asm volatile("s_waitcnt vmcnt(14)" ::: "memory"); else asm volatile("s_waitcnt vmcnt(15)" ::: "memory"); }
.LBB0_437:
	s_add_i32 s8, s25, 3
	s_min_u32 s4, s8, 33
	s_add_i32 s6, s4, 2
	s_sub_i32 s7, 37, s4
	s_and_b64 s[4:5], s[90:91], exec
	s_cselect_b32 s4, s6, s7
	s_lshl_b32 s5, s4, 6
	s_add_i32 s5, s5, s33
	s_add_i32 s4, s4, s31
	s_lshl_b32 s4, s4, 1
	s_mulk_i32 s5, 0xd00
	s_add_i32 s92, s4, s68
	s_or_b32 s4, s36, s5
	s_mov_b32 s5, s37
	s_lshl_b64 s[4:5], s[4:5], 1
	s_add_u32 s4, s16, s4
	s_addc_u32 s5, s17, s5
	global_load_dwordx4 v[56:59], v74, s[4:5]
	global_load_dwordx4 v[48:51], v74, s[4:5] offset:64
	s_mul_i32 s4, s92, 0x5000
	v_readlane_b32 s6, v254, 46
	s_mul_hi_u32 s5, s92, 0x5000
	s_add_u32 s4, s6, s4
	v_readlane_b32 s6, v254, 47
	s_addc_u32 s5, s6, s5
	s_mov_b64 s[6:7], s[4:5]
	s_add_u32 s4, s4, 0x2800
	s_addc_u32 s5, s5, 0
	global_load_dwordx4 v[84:87], v73, s[4:5] nt
	global_load_dwordx4 v[76:79], v73, s[4:5] offset:1024 nt
	global_load_dwordx4 v[88:91], v73, s[6:7] nt
	global_load_dwordx4 v[80:83], v73, s[6:7] offset:1024 nt
	global_load_dwordx2 v[144:145], v72, s[4:5] offset:2048 nt
	global_load_dwordx2 v[2:3], v72, s[6:7] offset:2048 nt
	s_lshl_b64 s[4:5], s[92:93], 8
	v_readlane_b32 s6, v254, 52
	v_readlane_b32 s7, v254, 53
	s_add_u32 s4, s6, s4
	s_addc_u32 s5, s7, s5
	global_load_dwordx4 v[72:75], v0, s[4:5]
	s_add_i32 s1, s1, s24
	s_and_b64 s[4:5], s[90:91], exec
	s_cselect_b32 s1, s8, s1
	ds_read_b128 v[104:107], v203 offset:11520
	s_lshl_b32 s4, s1, 3
	s_add_i32 s4, s34, s4
	v_mov_b32_e32 v0, s4
	ds_read_b32 v0, v0 offset:46080
	ds_read_b128 v[108:111], v203 offset:11584
	ds_read_b128 v[212:215], v203 offset:13824
	ds_read_b128 v[216:219], v203 offset:13888
	ds_read_b128 v[224:227], v203 offset:16128
	ds_read_b128 v[242:245], v203 offset:16192
	s_waitcnt lgkmcnt(6)
	v_mfma_f32_16x16x32_bf16 v[104:107], v[40:43], v[104:107], 0
	s_waitcnt vmcnt(63)
	v_lshlrev_b32_e32 v112, 16, v92
	v_and_b32_e32 v113, 0xffff0000, v92
	v_lshlrev_b32_e32 v114, 16, v93
	s_waitcnt lgkmcnt(4)
	v_mfma_f32_16x16x32_bf16 v[104:107], v[36:39], v[108:111], v[104:107]
	v_and_b32_e32 v115, 0xffff0000, v93
	v_pk_fma_f32 v[192:193], v[180:181], v[0:1], v[114:115] op_sel_hi:[1,0,1]
	v_pk_fma_f32 v[190:191], v[182:183], v[0:1], v[112:113] op_sel_hi:[1,0,1]
	s_waitcnt lgkmcnt(3)
	v_mfma_f32_16x16x32_bf16 v[108:111], v[40:43], v[212:215], 0
	v_lshlrev_b32_e32 v116, 16, v94
	v_and_b32_e32 v117, 0xffff0000, v94
	v_lshlrev_b32_e32 v118, 16, v95
	s_waitcnt lgkmcnt(2)
	v_mfma_f32_16x16x32_bf16 v[108:111], v[36:39], v[216:219], v[108:111]
	ds_read_b128 v[212:215], v203 offset:18432
	ds_read_b128 v[216:219], v203 offset:18496
	v_and_b32_e32 v119, 0xffff0000, v95
	v_pk_fma_f32 v[188:189], v[150:151], v[0:1], v[118:119] op_sel_hi:[1,0,1]
	v_pk_fma_f32 v[154:155], v[154:155], v[0:1], v[116:117] op_sel_hi:[1,0,1]
	s_waitcnt lgkmcnt(3)
	v_mfma_f32_16x16x32_bf16 v[112:115], v[40:43], v[224:227], 0
	s_waitcnt vmcnt(63)
	v_lshlrev_b32_e32 v150, 16, v64
	v_and_b32_e32 v151, 0xffff0000, v64
	v_lshlrev_b32_e32 v162, 16, v65
	s_waitcnt lgkmcnt(2)
	v_mfma_f32_16x16x32_bf16 v[112:115], v[36:39], v[242:245], v[112:115]
	ds_read_b128 v[224:227], v203 offset:20736
	ds_read_b128 v[242:245], v203 offset:20800
	v_and_b32_e32 v163, 0xffff0000, v65
	v_pk_fma_f32 v[186:187], v[148:149], v[0:1], v[162:163] op_sel_hi:[1,0,1]
	v_pk_fma_f32 v[182:183], v[152:153], v[0:1], v[150:151] op_sel_hi:[1,0,1]
	s_waitcnt lgkmcnt(3)
	v_mfma_f32_16x16x32_bf16 v[116:119], v[40:43], v[212:215], 0
	v_lshlrev_b32_e32 v152, 16, v66
	v_and_b32_e32 v153, 0xffff0000, v66
	s_waitcnt vmcnt(63)
	v_lshlrev_b32_e32 v168, 16, v142
	s_waitcnt lgkmcnt(2)
	v_mfma_f32_16x16x32_bf16 v[116:119], v[36:39], v[216:219], v[116:119]
	v_and_b32_e32 v169, 0xffff0000, v142
	v_lshlrev_b32_e32 v170, 16, v143
	s_waitcnt lgkmcnt(1)
	v_mfma_f32_16x16x32_bf16 v[148:151], v[40:43], v[224:227], 0
	v_and_b32_e32 v171, 0xffff0000, v143
	v_lshlrev_b32_e32 v162, 16, v67
	v_and_b32_e32 v163, 0xffff0000, v67
	s_waitcnt lgkmcnt(0)
	v_mfma_f32_16x16x32_bf16 v[148:151], v[36:39], v[242:245], v[148:151]
	v_fma_f32 v178, v160, v0, v152
	v_fma_f32 v179, v161, v0, v153
	v_lshlrev_b32_e32 v152, 16, v146
	v_and_b32_e32 v153, 0xffff0000, v146
	v_lshlrev_b32_e32 v160, 16, v147
	v_and_b32_e32 v161, 0xffff0000, v147
	s_waitcnt vmcnt(63)
	s_nop 0
	v_pk_fma_f32 v[150:151], v[62:63], v[150:151], v[170:171]
	v_pk_fma_f32 v[148:149], v[60:61], v[148:149], v[168:169]
	v_pk_fma_f32 v[162:163], v[184:185], v[0:1], v[162:163] op_sel_hi:[1,0,1]
	v_pk_fma_f32 v[164:165], v[156:157], v[0:1], v[160:161] op_sel_hi:[1,0,1]
	v_pk_fma_f32 v[180:181], v[158:159], v[0:1], v[152:153] op_sel_hi:[1,0,1]
	v_mov_b32_dpp v184, v148 row_newbcast:0 row_mask:0xf bank_mask:0xf bound_ctrl:1
	v_mov_b32_dpp v185, v148 row_newbcast:1 row_mask:0xf bank_mask:0xf bound_ctrl:1
	v_mov_b32_dpp v160, v149 row_newbcast:0 row_mask:0xf bank_mask:0xf bound_ctrl:1
	v_mov_b32_dpp v161, v149 row_newbcast:1 row_mask:0xf bank_mask:0xf bound_ctrl:1
	v_mov_b32_dpp v158, v150 row_newbcast:0 row_mask:0xf bank_mask:0xf bound_ctrl:1
	v_mov_b32_dpp v159, v150 row_newbcast:1 row_mask:0xf bank_mask:0xf bound_ctrl:1
	v_mov_b32_dpp v156, v151 row_newbcast:0 row_mask:0xf bank_mask:0xf bound_ctrl:1
	v_mov_b32_dpp v157, v151 row_newbcast:1 row_mask:0xf bank_mask:0xf bound_ctrl:1
	v_mov_b32_e32 v148, v194
	v_mov_b32_e32 v150, v196
	v_mov_b32_e32 v152, v199
	v_mov_b32_e32 v166, v198
	v_mov_b32_e32 v153, v200
	v_mov_b32_e32 v149, v195
	v_mov_b32_e32 v0, v120
	v_mov_b32_e32 v151, v197
	s_cmp_gt_u32 s25, 31
	s_cbranch_scc1 .LBB0_451
	v_cvt_pk_bf16_f32 v166, v190, v191
	v_cvt_pk_bf16_f32 v167, v192, v193
	ds_write_b64 v202, v[166:167]
	v_cvt_pk_bf16_f32 v166, v154, v155
	v_cvt_pk_bf16_f32 v167, v188, v189
	ds_write_b64 v202, v[166:167] offset:2304
	v_cvt_pk_bf16_f32 v166, v182, v183
	v_cvt_pk_bf16_f32 v167, v186, v187
	ds_write_b64 v202, v[166:167] offset:4608
	v_cvt_pk_bf16_f32 v166, v178, v179
	v_cvt_pk_bf16_f32 v167, v162, v163
	ds_write_b64 v202, v[166:167] offset:6912
	v_cvt_pk_bf16_f32 v166, v180, v181
	v_cvt_pk_bf16_f32 v167, v164, v165
	ds_write_b64 v202, v[166:167] offset:9216
	s_sub_i32 s4, s25, 17
	s_cmp_gt_u32 s4, 14
	s_mov_b64 s[10:11], -1
	s_cbranch_scc1 .LBB0_452

; #define LAS __attribute__((address_space(3)))
; template <bool GDN, int NT> __device__ __forceinline__ void scan_load(const Frame& F, int b, int h, int dir, const ScanLane& L, int s, ScanOps<NT>& o) {
;     ...
;         const char* zq = upin((const char*)F.Z + ((size_t)chunk_row0(b, cidx) * ZW + ZC_LQ + h * 64) * 2);
; #pragma unroll
;         for (int ks = 0; ks < 2; ++ks) { o.Qf[ks] = ldu<bf16x8>(zq + ks * 64, L.zq); o.Mf[ks] = o.Qf[ks]; }
;         const char* base = (const char*)F.PM + (size_t)ud * 20480;
;         const char* bO = upin(base); const char* bB = upin(base + 10240);
; #pragma unroll
;         for (int pr = 0; pr < 2; ++pr) { const v4u qb = ldun<v4u>(bB + pr * 1024, L.o16p), qo = ldun<v4u>(bO + pr * 1024, L.o16p);
;             o.bv[2 * pr] = (v2u){qb.x, qb.y}; o.bv[2 * pr + 1] = (v2u){qb.z, qb.w}; o.ov[2 * pr] = (v2u){qo.x, qo.y}; o.ov[2 * pr + 1] = (v2u){qo.z, qo.w}; }
;         o.bv[4] = ldun<v2u>(bB + 2048, L.o8); o.ov[4] = ldun<v2u>(bO + 2048, L.o8);
;     ...
;     const float gl = ((const LAS float*)(St + 4 * 80 * 72))[(dir ? (s < 4 ? 3 - s : 39 - s) : s) * 2 + dir];
;     f32x4 O[NT];
; #pragma unroll
;     for (int t = 0; t < NT; ++t) {
;         const LAS bf16_t* sp2 = Sb + (16 * t + lr) * 72 + 8 * lq;
;         const bf16x8 s0 = *(const LAS bf16x8*)sp2, s1 = *(const LAS bf16x8*)(sp2 + 32);
;         const f32x4 bv = unpack4(use.bv[t]), ov = unpack4(use.ov[t]);
;         if (GDN) {
;             f32x4 o = ov, sn = S[t] * gl + bv;
;             o = __builtin_amdgcn_mfma_f32_16x16x32_bf16(use.Qf[0], s0, o, 0, 0, 0); o = __builtin_amdgcn_mfma_f32_16x16x32_bf16(use.Qf[1], s1, o, 0, 0, 0);
;             sn = __builtin_amdgcn_mfma_f32_16x16x32_bf16(use.Mf[0], s0, sn, 0, 0, 0); sn = __builtin_amdgcn_mfma_f32_16x16x32_bf16(use.Mf[1], s1, sn, 0, 0, 0);
;             S[t] = sn; O[t] = o;
;         } else {
;             f32x4 o = {0.f, 0.f, 0.f, 0.f};
;             o = __builtin_amdgcn_mfma_f32_16x16x32_bf16(use.Qf[0], s0, o, 0, 0, 0); o = __builtin_amdgcn_mfma_f32_16x16x32_bf16(use.Qf[1], s1, o, 0, 0, 0);
;             S[t] = S[t] * gl + bv; O[t] = o * use.wi + ov; }
;     }
;     if (!GDN) {
; #pragma unroll
;         for (int i = 0; i < 4; ++i) { const float den = row16_bcast<0>(O[NT - 1][i]), fl = row16_bcast<1>(O[NT - 1][i]); const float dv = frcp(fmaxf(fabsf(den), fl));
; #pragma unroll
;             for (int t = 0; t < 4; ++t) O[t][i] *= dv; }
.LBB0_446:
	s_min_u32 s0, s3, 33
	s_add_i32 s4, s0, 2
	s_sub_i32 s5, 37, s0
	s_and_b64 s[0:1], s[90:91], exec
	s_cselect_b32 s0, s4, s5
	s_lshl_b32 s1, s0, 6
	s_add_i32 s1, s1, s33
	s_add_i32 s0, s0, s31
	s_lshl_b32 s0, s0, 1
	s_mulk_i32 s1, 0xd00
	s_add_i32 s92, s0, s68
	s_or_b32 s0, s36, s1
	s_mov_b32 s1, s37
	s_lshl_b64 s[0:1], s[0:1], 1
	s_add_u32 s0, s16, s0
	s_addc_u32 s1, s17, s1
	global_load_dwordx4 v[40:43], v150, s[0:1]
	global_load_dwordx4 v[36:39], v150, s[0:1] offset:64
	s_mul_i32 s0, s92, 0x5000
	v_readlane_b32 s4, v254, 46
	s_mul_hi_u32 s1, s92, 0x5000
	s_add_u32 s0, s4, s0
	v_readlane_b32 s4, v254, 47
	s_addc_u32 s1, s4, s1
	s_mov_b64 s[4:5], s[0:1]
	s_add_u32 s0, s0, 0x2800
	s_addc_u32 s1, s1, 0
	global_load_dwordx4 v[92:95], v149, s[0:1] nt
	global_load_dwordx4 v[64:67], v149, s[0:1] offset:1024 nt
	global_load_dwordx4 v[96:99], v149, s[4:5] nt
	global_load_dwordx4 v[68:71], v149, s[4:5] offset:1024 nt
	global_load_dwordx2 v[146:147], v148, s[0:1] offset:2048 nt
	global_load_dwordx2 v[142:143], v148, s[4:5] offset:2048 nt
	s_lshl_b64 s[0:1], s[92:93], 8
	v_readlane_b32 s4, v254, 52
	v_readlane_b32 s5, v254, 53
	s_add_u32 s0, s4, s0
	s_addc_u32 s1, s5, s1
	s_add_i32 s4, s24, 38
	global_load_dwordx4 v[60:63], v0, s[0:1]
	s_and_b64 s[0:1], s[90:91], exec
	s_cselect_b32 s0, s3, s4
	s_lshl_b32 s0, s0, 3
	s_add_i32 s0, s34, s0
	v_mov_b32_e32 v0, s0
	ds_read_b32 v0, v0 offset:46080
	ds_read_b128 v[104:107], v203
	ds_read_b128 v[108:111], v203 offset:64
	ds_read_b128 v[212:215], v203 offset:2304
	ds_read_b128 v[216:219], v203 offset:2368
	ds_read_b128 v[224:227], v203 offset:4608
	ds_read_b128 v[242:245], v203 offset:4672
	s_waitcnt lgkmcnt(5)
	v_mfma_f32_16x16x32_bf16 v[104:107], v[24:27], v[104:107], 0
	v_lshlrev_b32_e32 v112, 16, v44
	v_and_b32_e32 v113, 0xffff0000, v44
	v_lshlrev_b32_e32 v114, 16, v52
	s_waitcnt lgkmcnt(4)
	v_mfma_f32_16x16x32_bf16 v[104:107], v[20:23], v[108:111], v[104:107]
	v_and_b32_e32 v115, 0xffff0000, v52
	v_lshlrev_b32_e32 v52, 16, v53
	v_and_b32_e32 v53, 0xffff0000, v53
	v_pk_fma_f32 v[190:191], v[190:191], v[0:1], v[112:113] op_sel_hi:[1,0,1]
	v_lshlrev_b32_e32 v44, 16, v45
	s_nop 2
	v_pk_fma_f32 v[112:113], v[100:101], v[104:105], v[114:115]
	v_pk_fma_f32 v[114:115], v[102:103], v[106:107], v[52:53]
	v_and_b32_e32 v45, 0xffff0000, v45
	v_pk_fma_f32 v[192:193], v[192:193], v[0:1], v[44:45] op_sel_hi:[1,0,1]
	v_lshlrev_b32_e32 v52, 16, v46
	v_and_b32_e32 v53, 0xffff0000, v46
	v_lshlrev_b32_e32 v116, 16, v47
	v_and_b32_e32 v117, 0xffff0000, v47
	s_waitcnt lgkmcnt(3)
	v_mfma_f32_16x16x32_bf16 v[44:47], v[24:27], v[212:215], 0
	v_lshlrev_b32_e32 v118, 16, v54
	v_and_b32_e32 v119, 0xffff0000, v54
	v_lshlrev_b32_e32 v54, 16, v55
	s_waitcnt lgkmcnt(2)
	v_mfma_f32_16x16x32_bf16 v[44:47], v[20:23], v[216:219], v[44:47]
	ds_read_b128 v[212:215], v203 offset:6912
	ds_read_b128 v[216:219], v203 offset:6976
	v_and_b32_e32 v55, 0xffff0000, v55
	v_pk_fma_f32 v[154:155], v[154:155], v[0:1], v[52:53] op_sel_hi:[1,0,1]
	v_lshlrev_b32_e32 v108, 16, v28
	v_and_b32_e32 v109, 0xffff0000, v28
	v_lshlrev_b32_e32 v110, 16, v32
	s_nop 2
	v_pk_fma_f32 v[104:105], v[100:101], v[44:45], v[118:119]
	v_pk_fma_f32 v[106:107], v[102:103], v[46:47], v[54:55]
	s_waitcnt lgkmcnt(3)
	v_mfma_f32_16x16x32_bf16 v[44:47], v[24:27], v[224:227], 0
	v_and_b32_e32 v111, 0xffff0000, v32
	v_lshlrev_b32_e32 v32, 16, v33
	v_and_b32_e32 v33, 0xffff0000, v33
	s_waitcnt lgkmcnt(2)
	v_mfma_f32_16x16x32_bf16 v[44:47], v[20:23], v[242:245], v[44:47]
	ds_read_b128 v[224:227], v203 offset:9216
	ds_read_b128 v[242:245], v203 offset:9280
	v_fma_f32 v188, v188, v0, v116
	v_fma_f32 v189, v189, v0, v117
	v_pk_fma_f32 v[182:183], v[182:183], v[0:1], v[108:109] op_sel_hi:[1,0,1]
	v_lshlrev_b32_e32 v28, 16, v29
	v_and_b32_e32 v29, 0xffff0000, v29
	v_pk_fma_f32 v[186:187], v[186:187], v[0:1], v[28:29] op_sel_hi:[1,0,1]
	s_nop 1
	v_pk_fma_f32 v[108:109], v[100:101], v[44:45], v[110:111]
	v_pk_fma_f32 v[116:117], v[102:103], v[46:47], v[32:33]
	v_lshlrev_b32_e32 v32, 16, v30
	v_and_b32_e32 v33, 0xffff0000, v30
	v_lshlrev_b32_e32 v110, 16, v31
	v_and_b32_e32 v111, 0xffff0000, v31
	s_waitcnt lgkmcnt(3)
	v_mfma_f32_16x16x32_bf16 v[28:31], v[24:27], v[212:215], 0
	v_lshlrev_b32_e32 v118, 16, v34
	v_and_b32_e32 v119, 0xffff0000, v34
	v_lshlrev_b32_e32 v34, 16, v35
	s_waitcnt lgkmcnt(2)
	v_mfma_f32_16x16x32_bf16 v[28:31], v[20:23], v[216:219], v[28:31]
	v_and_b32_e32 v35, 0xffff0000, v35
	v_pk_fma_f32 v[178:179], v[178:179], v[0:1], v[32:33] op_sel_hi:[1,0,1]
	v_pk_fma_f32 v[162:163], v[162:163], v[0:1], v[110:111] op_sel_hi:[1,0,1]
	v_lshlrev_b32_e32 v110, 16, v138
	v_and_b32_e32 v111, 0xffff0000, v138
	s_nop 2
	v_pk_fma_f32 v[44:45], v[100:101], v[28:29], v[118:119]
	v_pk_fma_f32 v[46:47], v[102:103], v[30:31], v[34:35]
	s_waitcnt lgkmcnt(1)
	v_mfma_f32_16x16x32_bf16 v[24:27], v[24:27], v[224:227], 0
	v_lshlrev_b32_e32 v28, 16, v139
	v_and_b32_e32 v29, 0xffff0000, v139
	v_lshlrev_b32_e32 v52, 16, v140
	s_waitcnt lgkmcnt(0)
	v_mfma_f32_16x16x32_bf16 v[20:23], v[20:23], v[242:245], v[24:27]
	v_and_b32_e32 v53, 0xffff0000, v140
	v_lshlrev_b32_e32 v54, 16, v141
	v_and_b32_e32 v55, 0xffff0000, v141
	v_pk_fma_f32 v[164:165], v[164:165], v[0:1], v[54:55] op_sel_hi:[1,0,1]
	v_pk_fma_f32 v[180:181], v[180:181], v[0:1], v[52:53] op_sel_hi:[1,0,1]
	s_nop 2
	v_pk_fma_f32 v[20:21], v[100:101], v[20:21], v[110:111]
	v_pk_fma_f32 v[22:23], v[102:103], v[22:23], v[28:29]
	s_nop 0
	v_mov_b32_dpp v24, v20 row_newbcast:0 row_mask:0xf bank_mask:0xf bound_ctrl:1
	v_mov_b32_dpp v20, v20 row_newbcast:1 row_mask:0xf bank_mask:0xf bound_ctrl:1
	v_max_f32_e32 v20, v20, v20
	v_max_f32_e64 v24, |v24|, |v24|
	v_max_f32_e32 v20, v24, v20
	v_rcp_f32_e32 v28, v20
	s_nop 0
	v_mov_b32_dpp v20, v21 row_newbcast:0 row_mask:0xf bank_mask:0xf bound_ctrl:1
	v_mov_b32_dpp v21, v21 row_newbcast:1 row_mask:0xf bank_mask:0xf bound_ctrl:1
	v_max_f32_e32 v21, v21, v21
	v_max_f32_e64 v20, |v20|, |v20|
	v_max_f32_e32 v20, v20, v21
	v_mov_b32_dpp v21, v22 row_newbcast:0 row_mask:0xf bank_mask:0xf bound_ctrl:1
	v_mov_b32_dpp v22, v22 row_newbcast:1 row_mask:0xf bank_mask:0xf bound_ctrl:1
	v_max_f32_e32 v22, v22, v22
	v_max_f32_e64 v21, |v21|, |v21|
	v_max_f32_e32 v21, v21, v22
	v_rcp_f32_e32 v30, v21
	v_mov_b32_dpp v22, v23 row_newbcast:1 row_mask:0xf bank_mask:0xf bound_ctrl:1
	v_mov_b32_dpp v21, v23 row_newbcast:0 row_mask:0xf bank_mask:0xf bound_ctrl:1
	v_max_f32_e32 v22, v22, v22
	v_max_f32_e64 v21, |v21|, |v21|
	v_max_f32_e32 v21, v21, v22
	v_rcp_f32_e32 v31, v21
	v_rcp_f32_e32 v29, v20
	v_pk_mul_f32 v[20:21], v[114:115], v[30:31]
	v_pk_mul_f32 v[24:25], v[112:113], v[28:29]
	v_pk_mul_f32 v[110:111], v[106:107], v[30:31]
	v_pk_mul_f32 v[104:105], v[104:105], v[28:29]
	v_pk_mul_f32 v[22:23], v[116:117], v[30:31]
	v_pk_mul_f32 v[26:27], v[108:109], v[28:29]
	v_pk_mul_f32 v[108:109], v[46:47], v[30:31]
	v_pk_mul_f32 v[106:107], v[44:45], v[28:29]
	s_branch .LBB0_456

; #define LAS __attribute__((address_space(3)))
; template <bool GDN, int NT> __device__ __forceinline__ void scan_load(const Frame& F, int b, int h, int dir, const ScanLane& L, int s, ScanOps<NT>& o) {
;     ...
;     if (GDN) {
;         const char* base = (const char*)F.PG + (size_t)ud * 32768;
;         const char* bM = upin(base); const char* bB = upin(base + 8192); const char* bQ = upin(base + 16384); const char* bO = upin(base + 24576);
; #pragma unroll
;     ...
;     if (s < 36) {
; #pragma unroll
;         for (int t = 0; t < NT; ++t) *(LAS v2u*)(Sb + (16 * t + lr) * 72 + 16 * wq + 4 * lq) = pack4(S[t]); }
;     if (s == 21 || s == 3) asm volatile("s_waitcnt vmcnt(0)" ::: "memory");
;     else if (scan_needfin(s - 1)) { if (GDN) asm volatile("s_waitcnt vmcnt(14)" ::: "memory"); else asm volatile("s_waitcnt vmcnt(15)" ::: "memory"); }
;     else { if (GDN) asm volatile("s_waitcnt vmcnt(8)" ::: "memory"); else asm volatile("s_waitcnt vmcnt(9)" ::: "memory"); }
;     __syncthreads();
;     if (s > 0) {
;         const int sp = s - 1;
;         if (sp == 20 || sp == 2) { asm volatile("s_waitcnt vmcnt(0)" ::: "memory"); scan_fin_load<GDN>(F, b, h, dir, L, sp, PEND, fin); }
;         if (!nofin) scan_finish<GDN>(F, b, h, dir, L, sp, PEND, Oprev, fin);
;     }
;     if (s == 36) return false;
;     if (scan_needfin(s) && ko != 1 && ko != 3) scan_fin_load<GDN>(F, b, h, dir, L, s + 1, PEND, fin);
;     if (ko != 1 && ko != 2) scan_load<GDN, NT>(F, b, h, dir, L, s < 34 ? s + 2 : 35, ld);
;     const float gl = ((const LAS float*)(St + 4 * 80 * 72))[(dir ? (s < 4 ? 3 - s : 39 - s) : s) * 2 + dir];
;     f32x4 O[NT];
; #pragma unroll
;     for (int t = 0; t < NT; ++t) {
;         const LAS bf16_t* sp2 = Sb + (16 * t + lr) * 72 + 8 * lq;
;         const bf16x8 s0 = *(const LAS bf16x8*)sp2, s1 = *(const LAS bf16x8*)(sp2 + 32);
;         const f32x4 bv = unpack4(use.bv[t]), ov = unpack4(use.ov[t]);
;         if (GDN) {
;             f32x4 o = ov, sn = S[t] * gl + bv;
;             o = __builtin_amdgcn_mfma_f32_16x16x32_bf16(use.Qf[0], s0, o, 0, 0, 0); o = __builtin_amdgcn_mfma_f32_16x16x32_bf16(use.Qf[1], s1, o, 0, 0, 0);
;             sn = __builtin_amdgcn_mfma_f32_16x16x32_bf16(use.Mf[0], s0, sn, 0, 0, 0); sn = __builtin_amdgcn_mfma_f32_16x16x32_bf16(use.Mf[1], s1, sn, 0, 0, 0);
;             S[t] = sn; O[t] = o;
.LBB0_481:
	s_add_i32 s0, s23, 5
	s_min_u32 s3, s0, 33
	s_add_i32 s6, s3, 2
	s_sub_i32 s3, 37, s3
	s_and_b64 s[4:5], s[90:91], exec
	s_cselect_b32 s3, s6, s3
	s_add_i32 s3, s3, s30
	s_lshl_b32 s3, s3, 1
	s_add_i32 s4, s3, s68
	s_ashr_i32 s5, s4, 31
	s_lshl_b64 s[4:5], s[4:5], 15
	s_add_u32 s4, s35, s4
	s_addc_u32 s5, s43, s5
	s_add_u32 s8, s4, 0x2000
	s_addc_u32 s9, s5, 0
	s_add_u32 s10, s4, 0x4000
	s_addc_u32 s11, s5, 0
	s_mov_b64 s[6:7], s[4:5]
	s_add_u32 s4, s4, 0x6000
	s_addc_u32 s5, s5, 0
	global_load_dwordx4 v[70:73], v18, s[8:9] nt
	global_load_dwordx4 v[66:69], v18, s[4:5] nt
	global_load_dwordx4 v[22:25], v18, s[8:9] offset:1024 nt
	s_nop 0
	global_load_dwordx4 v[18:21], v18, s[4:5] offset:1024 nt
	s_add_i32 s3, s22, 37
	s_and_b64 s[4:5], s[90:91], exec
	s_cselect_b32 s0, s0, s3
	s_lshl_b32 s0, s0, 3
	s_add_i32 s0, s34, s0
	v_lshl_add_u64 v[146:147], s[6:7], 0, v[0:1]
	v_lshl_add_u64 v[148:149], s[10:11], 0, v[0:1]
	v_mov_b32_e32 v0, s0
	ds_read_b32 v0, v0 offset:46080
	ds_read_b128 v[98:101], v200 offset:11520
	ds_read_b128 v[102:105], v200 offset:11584
	ds_read_b128 v[212:215], v200 offset:13824
	ds_read_b128 v[216:219], v200 offset:13888
	ds_read_b128 v[224:227], v200 offset:16128
	ds_read_b128 v[242:245], v200 offset:16192
	s_waitcnt vmcnt(63)
	v_lshlrev_b32_e32 v110, 16, v94
	v_and_b32_e32 v111, 0xffff0000, v94
	v_lshlrev_b32_e32 v112, 16, v95
	v_and_b32_e32 v113, 0xffff0000, v95
	s_waitcnt vmcnt(63)
	v_lshlrev_b32_e32 v106, 16, v86
	v_and_b32_e32 v107, 0xffff0000, v86
	v_lshlrev_b32_e32 v108, 16, v87
	v_and_b32_e32 v109, 0xffff0000, v87
	s_waitcnt lgkmcnt(6)
	v_pk_fma_f32 v[112:113], v[128:129], v[0:1], v[112:113] op_sel_hi:[1,0,1]
	v_pk_fma_f32 v[110:111], v[126:127], v[0:1], v[110:111] op_sel_hi:[1,0,1]
	s_waitcnt lgkmcnt(5)
	v_mfma_f32_16x16x32_bf16 v[106:109], v[46:49], v[98:101], v[106:109]
	s_mov_b64 s[6:7], 0x400
	v_lshl_add_u64 v[150:151], v[146:147], 0, s[6:7]
	v_lshl_add_u64 v[152:153], v[148:149], 0, s[6:7]
	v_mfma_f32_16x16x32_bf16 v[98:101], v[30:33], v[98:101], v[110:113]
	s_add_i32 s3, s22, -6
	s_mov_b64 s[20:21], 0
	s_waitcnt lgkmcnt(4)
	v_mfma_f32_16x16x32_bf16 v[130:133], v[34:37], v[102:105], v[106:109]
	v_lshlrev_b32_e32 v110, 16, v96
	v_and_b32_e32 v111, 0xffff0000, v96
	v_lshlrev_b32_e32 v112, 16, v97
	v_mfma_f32_16x16x32_bf16 v[126:129], v[26:29], v[102:105], v[98:101]
	s_nop 2
	v_and_b32_e32 v113, 0xffff0000, v97
	v_lshlrev_b32_e32 v106, 16, v88
	v_and_b32_e32 v107, 0xffff0000, v88
	v_lshlrev_b32_e32 v108, 16, v89
	v_and_b32_e32 v109, 0xffff0000, v89
	v_pk_fma_f32 v[112:113], v[124:125], v[0:1], v[112:113] op_sel_hi:[1,0,1]
	v_pk_fma_f32 v[110:111], v[122:123], v[0:1], v[110:111] op_sel_hi:[1,0,1]
	s_waitcnt lgkmcnt(3)
	v_mfma_f32_16x16x32_bf16 v[106:109], v[46:49], v[212:215], v[106:109]
	v_mfma_f32_16x16x32_bf16 v[98:101], v[30:33], v[212:215], v[110:113]
	s_waitcnt lgkmcnt(2)
	v_mfma_f32_16x16x32_bf16 v[134:137], v[34:37], v[216:219], v[106:109]
	s_waitcnt vmcnt(63)
	v_lshlrev_b32_e32 v110, 16, v78
	v_and_b32_e32 v111, 0xffff0000, v78
	v_lshlrev_b32_e32 v112, 16, v79
	v_mfma_f32_16x16x32_bf16 v[122:125], v[26:29], v[216:219], v[98:101]
	ds_read_b128 v[212:215], v200 offset:18432
	ds_read_b128 v[216:219], v200 offset:18496
	s_nop 2
	v_and_b32_e32 v113, 0xffff0000, v79
	s_waitcnt vmcnt(63)
	v_lshlrev_b32_e32 v106, 16, v74
	v_and_b32_e32 v107, 0xffff0000, v74
	v_lshlrev_b32_e32 v108, 16, v75
	v_and_b32_e32 v109, 0xffff0000, v75
	v_pk_fma_f32 v[112:113], v[116:117], v[0:1], v[112:113] op_sel_hi:[1,0,1]
	v_pk_fma_f32 v[110:111], v[114:115], v[0:1], v[110:111] op_sel_hi:[1,0,1]
	s_waitcnt lgkmcnt(3)
	v_mfma_f32_16x16x32_bf16 v[106:109], v[46:49], v[224:227], v[106:109]
	v_mfma_f32_16x16x32_bf16 v[98:101], v[30:33], v[224:227], v[110:113]
	s_waitcnt lgkmcnt(2)
	v_mfma_f32_16x16x32_bf16 v[138:141], v[34:37], v[242:245], v[106:109]
	s_nop 0
	v_lshlrev_b32_e32 v110, 16, v80
	v_and_b32_e32 v111, 0xffff0000, v80
	v_lshlrev_b32_e32 v112, 16, v81
	v_mfma_f32_16x16x32_bf16 v[114:117], v[26:29], v[242:245], v[98:101]
	s_nop 2
	v_and_b32_e32 v113, 0xffff0000, v81
	v_lshlrev_b32_e32 v106, 16, v76
	v_and_b32_e32 v107, 0xffff0000, v76
	v_lshlrev_b32_e32 v108, 16, v77
	v_and_b32_e32 v109, 0xffff0000, v77
	v_pk_fma_f32 v[112:113], v[120:121], v[0:1], v[112:113] op_sel_hi:[1,0,1]
	v_pk_fma_f32 v[110:111], v[118:119], v[0:1], v[110:111] op_sel_hi:[1,0,1]
	s_waitcnt lgkmcnt(1)
	v_mfma_f32_16x16x32_bf16 v[106:109], v[46:49], v[212:215], v[106:109]
	v_mfma_f32_16x16x32_bf16 v[98:101], v[30:33], v[212:215], v[110:113]
	s_waitcnt lgkmcnt(0)
	v_mfma_f32_16x16x32_bf16 v[142:145], v[34:37], v[216:219], v[106:109]
	v_mfma_f32_16x16x32_bf16 v[118:121], v[26:29], v[216:219], v[98:101]

; #define LAS __attribute__((address_space(3)))
; template <bool GDN, int NT> __device__ __forceinline__ void scan_load(const Frame& F, int b, int h, int dir, const ScanLane& L, int s, ScanOps<NT>& o) {
;     ...
;     if (GDN) {
;         const char* base = (const char*)F.PG + (size_t)ud * 32768;
;         const char* bM = upin(base); const char* bB = upin(base + 8192); const char* bQ = upin(base + 16384); const char* bO = upin(base + 24576);
; #pragma unroll
;     ...
;     if (s < 36) {
; #pragma unroll
;         for (int t = 0; t < NT; ++t) *(LAS v2u*)(Sb + (16 * t + lr) * 72 + 16 * wq + 4 * lq) = pack4(S[t]); }
;     if (s == 21 || s == 3) asm volatile("s_waitcnt vmcnt(0)" ::: "memory");
;     else if (scan_needfin(s - 1)) { if (GDN) asm volatile("s_waitcnt vmcnt(14)" ::: "memory"); else asm volatile("s_waitcnt vmcnt(15)" ::: "memory"); }
;     else { if (GDN) asm volatile("s_waitcnt vmcnt(8)" ::: "memory"); else asm volatile("s_waitcnt vmcnt(9)" ::: "memory"); }
;     __syncthreads();
;     if (s > 0) {
;         const int sp = s - 1;
;         if (sp == 20 || sp == 2) { asm volatile("s_waitcnt vmcnt(0)" ::: "memory"); scan_fin_load<GDN>(F, b, h, dir, L, sp, PEND, fin); }
;         if (!nofin) scan_finish<GDN>(F, b, h, dir, L, sp, PEND, Oprev, fin);
;     }
;     if (s == 36) return false;
;     if (scan_needfin(s) && ko != 1 && ko != 3) scan_fin_load<GDN>(F, b, h, dir, L, s + 1, PEND, fin);
;     if (ko != 1 && ko != 2) scan_load<GDN, NT>(F, b, h, dir, L, s < 34 ? s + 2 : 35, ld);
;     const float gl = ((const LAS float*)(St + 4 * 80 * 72))[(dir ? (s < 4 ? 3 - s : 39 - s) : s) * 2 + dir];
;     f32x4 O[NT];
; #pragma unroll
;     for (int t = 0; t < NT; ++t) {
;         const LAS bf16_t* sp2 = Sb + (16 * t + lr) * 72 + 8 * lq;
;         const bf16x8 s0 = *(const LAS bf16x8*)sp2, s1 = *(const LAS bf16x8*)(sp2 + 32);
;         const f32x4 bv = unpack4(use.bv[t]), ov = unpack4(use.ov[t]);
;         if (GDN) {
;             f32x4 o = ov, sn = S[t] * gl + bv;
;             o = __builtin_amdgcn_mfma_f32_16x16x32_bf16(use.Qf[0], s0, o, 0, 0, 0); o = __builtin_amdgcn_mfma_f32_16x16x32_bf16(use.Qf[1], s1, o, 0, 0, 0);
;             sn = __builtin_amdgcn_mfma_f32_16x16x32_bf16(use.Mf[0], s0, sn, 0, 0, 0); sn = __builtin_amdgcn_mfma_f32_16x16x32_bf16(use.Mf[1], s1, sn, 0, 0, 0);
;             S[t] = sn; O[t] = o;
.LBB0_496:
	s_min_u32 s1, s23, 33
	s_add_i32 s1, s1, 2
	s_and_b64 s[4:5], exec, s[10:11]
	s_cselect_b32 s3, 3, 39
	s_sub_i32 s3, s3, s1
	s_and_b64 s[4:5], s[90:91], exec
	s_cselect_b32 s1, s1, s3
	s_add_i32 s1, s1, s30
	s_lshl_b32 s1, s1, 1
	s_add_i32 s4, s1, s68
	s_ashr_i32 s5, s4, 31
	s_lshl_b64 s[4:5], s[4:5], 15
	s_add_u32 s4, s35, s4
	s_addc_u32 s5, s43, s5
	s_add_u32 s8, s4, 0x2000
	s_addc_u32 s9, s5, 0
	s_add_u32 s12, s4, 0x4000
	s_addc_u32 s13, s5, 0
	s_mov_b64 s[6:7], s[4:5]
	s_add_u32 s4, s4, 0x6000
	s_addc_u32 s5, s5, 0
	global_load_dwordx4 v[30:33], v146, s[6:7] nt
	global_load_dwordx4 v[46:49], v146, s[12:13] nt
	global_load_dwordx4 v[26:29], v146, s[6:7] offset:1024 nt
	global_load_dwordx4 v[34:37], v146, s[12:13] offset:1024 nt
	global_load_dwordx4 v[94:97], v0, s[8:9] nt
	global_load_dwordx4 v[86:89], v0, s[4:5] nt
	global_load_dwordx4 v[78:81], v0, s[8:9] offset:1024 nt
	global_load_dwordx4 v[74:77], v0, s[4:5] offset:1024 nt
	s_cmp_gt_u32 s23, 3
	s_cselect_b32 s1, 39, 3
	s_add_i32 s1, s1, s22
	s_add_i32 s1, s1, 3
	s_and_b64 s[4:5], s[90:91], exec
	s_cselect_b32 s1, s23, s1
	s_lshl_b32 s1, s1, 3
	s_add_i32 s1, s34, s1
	v_mov_b32_e32 v0, s1
	ds_read_b32 v0, v0 offset:46080
	v_add_u32_e32 v146, v198, v155
	ds_read_b128 v[134:137], v146
	ds_read_b128 v[138:141], v146 offset:64
	ds_read_b128 v[212:215], v146 offset:2304
	ds_read_b128 v[216:219], v146 offset:2368
	ds_read_b128 v[224:227], v146 offset:4608
	ds_read_b128 v[242:245], v146 offset:4672
	s_waitcnt vmcnt(63)
	v_lshlrev_b32_e32 v142, 16, v90
	v_and_b32_e32 v143, 0xffff0000, v90
	v_lshlrev_b32_e32 v90, 16, v91
	v_and_b32_e32 v91, 0xffff0000, v91
	s_waitcnt vmcnt(63)
	v_lshlrev_b32_e32 v130, 16, v82
	v_and_b32_e32 v131, 0xffff0000, v82
	v_lshlrev_b32_e32 v132, 16, v83
	v_and_b32_e32 v133, 0xffff0000, v83
	s_waitcnt lgkmcnt(6)
	v_pk_fma_f32 v[128:129], v[128:129], v[0:1], v[90:91] op_sel_hi:[1,0,1]
	v_pk_fma_f32 v[126:127], v[126:127], v[0:1], v[142:143] op_sel_hi:[1,0,1]
	s_waitcnt lgkmcnt(5)
	v_mfma_f32_16x16x32_bf16 v[130:133], v[58:61], v[134:137], v[130:133]
	v_lshlrev_b32_e32 v82, 16, v84
	v_and_b32_e32 v83, 0xffff0000, v84
	v_lshlrev_b32_e32 v84, 16, v85
	v_mfma_f32_16x16x32_bf16 v[126:129], v[42:45], v[134:137], v[126:129]
	v_and_b32_e32 v85, 0xffff0000, v85
	v_lshlrev_b32_e32 v90, 16, v92
	v_and_b32_e32 v91, 0xffff0000, v92
	s_waitcnt lgkmcnt(4)
	v_mfma_f32_16x16x32_bf16 v[130:133], v[50:53], v[138:141], v[130:133]
	v_lshlrev_b32_e32 v92, 16, v93
	v_and_b32_e32 v93, 0xffff0000, v93
	v_pk_fma_f32 v[92:93], v[124:125], v[0:1], v[92:93] op_sel_hi:[1,0,1]
	v_mfma_f32_16x16x32_bf16 v[126:129], v[38:41], v[138:141], v[126:129]
	v_pk_fma_f32 v[90:91], v[122:123], v[0:1], v[90:91] op_sel_hi:[1,0,1]
	s_waitcnt lgkmcnt(3)
	v_mfma_f32_16x16x32_bf16 v[82:85], v[58:61], v[212:215], v[82:85]
	s_waitcnt lgkmcnt(2)
	v_mfma_f32_16x16x32_bf16 v[134:137], v[50:53], v[216:219], v[82:85]
	v_mfma_f32_16x16x32_bf16 v[82:85], v[42:45], v[212:215], v[90:93]
	s_waitcnt vmcnt(63)
	v_lshlrev_b32_e32 v138, 16, v54
	v_and_b32_e32 v139, 0xffff0000, v54
	v_lshlrev_b32_e32 v140, 16, v55
	v_mfma_f32_16x16x32_bf16 v[122:125], v[38:41], v[216:219], v[82:85]
	ds_read_b128 v[212:215], v146 offset:6912
	ds_read_b128 v[216:219], v146 offset:6976
	s_nop 2
	v_lshlrev_b32_e32 v142, 16, v62
	v_and_b32_e32 v143, 0xffff0000, v62
	v_lshlrev_b32_e32 v62, 16, v63
	v_and_b32_e32 v63, 0xffff0000, v63
	v_and_b32_e32 v141, 0xffff0000, v55
	v_pk_fma_f32 v[116:117], v[116:117], v[0:1], v[62:63] op_sel_hi:[1,0,1]
	v_pk_fma_f32 v[114:115], v[114:115], v[0:1], v[142:143] op_sel_hi:[1,0,1]
	s_waitcnt lgkmcnt(3)
	v_mfma_f32_16x16x32_bf16 v[138:141], v[58:61], v[224:227], v[138:141]
	v_lshlrev_b32_e32 v62, 16, v64
	v_and_b32_e32 v63, 0xffff0000, v64
	v_lshlrev_b32_e32 v64, 16, v65
	v_mfma_f32_16x16x32_bf16 v[82:85], v[42:45], v[224:227], v[114:117]
	v_and_b32_e32 v65, 0xffff0000, v65
	v_lshlrev_b32_e32 v54, 16, v56
	v_and_b32_e32 v55, 0xffff0000, v56
	s_waitcnt lgkmcnt(2)
	v_mfma_f32_16x16x32_bf16 v[138:141], v[50:53], v[242:245], v[138:141]
	v_lshlrev_b32_e32 v56, 16, v57
	v_and_b32_e32 v57, 0xffff0000, v57
	v_pk_fma_f32 v[64:65], v[120:121], v[0:1], v[64:65] op_sel_hi:[1,0,1]
	v_mfma_f32_16x16x32_bf16 v[114:117], v[38:41], v[242:245], v[82:85]
	s_nop 2
	v_pk_fma_f32 v[62:63], v[118:119], v[0:1], v[62:63] op_sel_hi:[1,0,1]
	s_waitcnt lgkmcnt(1)
	v_mfma_f32_16x16x32_bf16 v[54:57], v[58:61], v[212:215], v[54:57]
	v_mfma_f32_16x16x32_bf16 v[42:45], v[42:45], v[212:215], v[62:65]
	s_waitcnt lgkmcnt(0)
	v_mfma_f32_16x16x32_bf16 v[142:145], v[50:53], v[216:219], v[54:57]
	v_mfma_f32_16x16x32_bf16 v[118:121], v[38:41], v[216:219], v[42:45]

; #define LAS __attribute__((address_space(3)))
; template <bool GDN, int NT> __device__ __forceinline__ void scan_load(const Frame& F, int b, int h, int dir, const ScanLane& L, int s, ScanOps<NT>& o) {
;     ...
;     if (GDN) {
;         const char* base = (const char*)F.PG + (size_t)ud * 32768;
;         const char* bM = upin(base); const char* bB = upin(base + 8192); const char* bQ = upin(base + 16384); const char* bO = upin(base + 24576);
; #pragma unroll
;     ...
;     if (s < 36) {
; #pragma unroll
;         for (int t = 0; t < NT; ++t) *(LAS v2u*)(Sb + (16 * t + lr) * 72 + 16 * wq + 4 * lq) = pack4(S[t]); }
;     if (s == 21 || s == 3) asm volatile("s_waitcnt vmcnt(0)" ::: "memory");
;     else if (scan_needfin(s - 1)) { if (GDN) asm volatile("s_waitcnt vmcnt(14)" ::: "memory"); else asm volatile("s_waitcnt vmcnt(15)" ::: "memory"); }
;     else { if (GDN) asm volatile("s_waitcnt vmcnt(8)" ::: "memory"); else asm volatile("s_waitcnt vmcnt(9)" ::: "memory"); }
;     __syncthreads();
;     if (s > 0) {
;         const int sp = s - 1;
;         if (sp == 20 || sp == 2) { asm volatile("s_waitcnt vmcnt(0)" ::: "memory"); scan_fin_load<GDN>(F, b, h, dir, L, sp, PEND, fin); }
;         if (!nofin) scan_finish<GDN>(F, b, h, dir, L, sp, PEND, Oprev, fin);
;     }
;     if (s == 36) return false;
;     if (scan_needfin(s) && ko != 1 && ko != 3) scan_fin_load<GDN>(F, b, h, dir, L, s + 1, PEND, fin);
;     if (ko != 1 && ko != 2) scan_load<GDN, NT>(F, b, h, dir, L, s < 34 ? s + 2 : 35, ld);
;     const float gl = ((const LAS float*)(St + 4 * 80 * 72))[(dir ? (s < 4 ? 3 - s : 39 - s) : s) * 2 + dir];
;     f32x4 O[NT];
; #pragma unroll
;     for (int t = 0; t < NT; ++t) {
;         const LAS bf16_t* sp2 = Sb + (16 * t + lr) * 72 + 8 * lq;
;         const bf16x8 s0 = *(const LAS bf16x8*)sp2, s1 = *(const LAS bf16x8*)(sp2 + 32);
;         const f32x4 bv = unpack4(use.bv[t]), ov = unpack4(use.ov[t]);
;         if (GDN) {
;             f32x4 o = ov, sn = S[t] * gl + bv;
;             o = __builtin_amdgcn_mfma_f32_16x16x32_bf16(use.Qf[0], s0, o, 0, 0, 0); o = __builtin_amdgcn_mfma_f32_16x16x32_bf16(use.Qf[1], s1, o, 0, 0, 0);
;             sn = __builtin_amdgcn_mfma_f32_16x16x32_bf16(use.Mf[0], s0, sn, 0, 0, 0); sn = __builtin_amdgcn_mfma_f32_16x16x32_bf16(use.Mf[1], s1, sn, 0, 0, 0);
;             S[t] = sn; O[t] = o;
.LBB0_531:
	s_min_u32 s1, s4, 33
	s_add_i32 s8, s1, 2
	s_and_b64 s[6:7], exec, s[10:11]
	s_cselect_b32 s1, 3, 39
	s_sub_i32 s9, s1, s8
	s_and_b64 s[6:7], s[90:91], exec
	s_cselect_b32 s6, s8, s9
	s_add_i32 s6, s6, s30
	s_lshl_b32 s6, s6, 1
	s_add_i32 s6, s6, s68
	s_ashr_i32 s7, s6, 31
	s_lshl_b64 s[6:7], s[6:7], 15
	s_add_u32 s6, s35, s6
	s_addc_u32 s7, s43, s7
	s_add_u32 s10, s6, 0x2000
	s_addc_u32 s11, s7, 0
	s_add_u32 s12, s6, 0x4000
	s_addc_u32 s13, s7, 0
	s_mov_b64 s[8:9], s[6:7]
	s_add_u32 s6, s6, 0x6000
	s_addc_u32 s7, s7, 0
	global_load_dwordx4 v[42:45], v50, s[8:9] nt
	global_load_dwordx4 v[58:61], v50, s[12:13] nt
	global_load_dwordx4 v[38:41], v50, s[8:9] offset:1024 nt
	s_nop 0
	global_load_dwordx4 v[50:53], v50, s[12:13] offset:1024 nt
	s_nop 0
	global_load_dwordx4 v[90:93], v0, s[10:11] nt
	global_load_dwordx4 v[82:85], v0, s[6:7] nt
	global_load_dwordx4 v[62:65], v0, s[10:11] offset:1024 nt
	global_load_dwordx4 v[54:57], v0, s[6:7] offset:1024 nt
	s_add_i32 s5, s5, 2
	s_and_b64 s[6:7], s[90:91], exec
	s_cselect_b32 s5, s4, s5
	s_lshl_b32 s6, s5, 3
	s_add_i32 s6, s34, s6
	v_mov_b32_e32 v0, s6
	ds_read_b32 v0, v0 offset:46080
	v_add_u32_e32 v200, v198, v155
	ds_read_b128 v[134:137], v200 offset:11520
	ds_read_b128 v[138:141], v200 offset:11584
	ds_read_b128 v[212:215], v200 offset:13824
	ds_read_b128 v[216:219], v200 offset:13888
	ds_read_b128 v[224:227], v200 offset:16128
	ds_read_b128 v[242:245], v200 offset:16192
	s_waitcnt vmcnt(63)
	v_lshlrev_b32_e32 v142, 16, v70
	v_and_b32_e32 v143, 0xffff0000, v70
	v_lshlrev_b32_e32 v144, 16, v71
	v_and_b32_e32 v145, 0xffff0000, v71
	s_waitcnt vmcnt(63)
	v_lshlrev_b32_e32 v130, 16, v66
	v_and_b32_e32 v131, 0xffff0000, v66
	v_lshlrev_b32_e32 v132, 16, v67
	v_and_b32_e32 v133, 0xffff0000, v67
	s_waitcnt lgkmcnt(6)
	v_pk_fma_f32 v[128:129], v[128:129], v[0:1], v[144:145] op_sel_hi:[1,0,1]
	v_pk_fma_f32 v[126:127], v[126:127], v[0:1], v[142:143] op_sel_hi:[1,0,1]
	s_waitcnt lgkmcnt(5)
	v_mfma_f32_16x16x32_bf16 v[130:133], v[110:113], v[134:137], v[130:133]
	v_lshlrev_b32_e32 v146, 16, v72
	v_and_b32_e32 v147, 0xffff0000, v72
	v_lshlrev_b32_e32 v148, 16, v73
	v_mfma_f32_16x16x32_bf16 v[126:129], v[102:105], v[134:137], v[126:129]
	v_and_b32_e32 v149, 0xffff0000, v73
	v_lshlrev_b32_e32 v134, 16, v68
	v_and_b32_e32 v135, 0xffff0000, v68
	s_waitcnt lgkmcnt(4)
	v_mfma_f32_16x16x32_bf16 v[130:133], v[106:109], v[138:141], v[130:133]
	v_lshlrev_b32_e32 v136, 16, v69
	v_and_b32_e32 v137, 0xffff0000, v69
	v_pk_fma_f32 v[124:125], v[124:125], v[0:1], v[148:149] op_sel_hi:[1,0,1]
	v_mfma_f32_16x16x32_bf16 v[126:129], v[98:101], v[138:141], v[126:129]
	v_pk_fma_f32 v[122:123], v[122:123], v[0:1], v[146:147] op_sel_hi:[1,0,1]
	v_lshlrev_b32_e32 v150, 16, v22
	s_waitcnt lgkmcnt(3)
	v_mfma_f32_16x16x32_bf16 v[134:137], v[110:113], v[212:215], v[134:137]
	v_and_b32_e32 v151, 0xffff0000, v22
	v_lshlrev_b32_e32 v152, 16, v23
	v_and_b32_e32 v153, 0xffff0000, v23
	v_mfma_f32_16x16x32_bf16 v[122:125], v[102:105], v[212:215], v[122:125]
	v_lshlrev_b32_e32 v138, 16, v18
	v_and_b32_e32 v139, 0xffff0000, v18
	v_lshlrev_b32_e32 v140, 16, v19
	s_waitcnt lgkmcnt(2)
	v_mfma_f32_16x16x32_bf16 v[134:137], v[106:109], v[216:219], v[134:137]
	v_and_b32_e32 v141, 0xffff0000, v19
	v_pk_fma_f32 v[116:117], v[116:117], v[0:1], v[152:153] op_sel_hi:[1,0,1]
	v_pk_fma_f32 v[114:115], v[114:115], v[0:1], v[150:151] op_sel_hi:[1,0,1]
	v_mfma_f32_16x16x32_bf16 v[122:125], v[98:101], v[216:219], v[122:125]
	ds_read_b128 v[212:215], v200 offset:18432
	ds_read_b128 v[216:219], v200 offset:18496
	v_lshlrev_b32_e32 v166, 16, v24
	v_and_b32_e32 v167, 0xffff0000, v24
	s_waitcnt lgkmcnt(3)
	v_mfma_f32_16x16x32_bf16 v[138:141], v[110:113], v[224:227], v[138:141]
	v_lshlrev_b32_e32 v168, 16, v25
	v_and_b32_e32 v169, 0xffff0000, v25
	v_pk_fma_f32 v[120:121], v[120:121], v[0:1], v[168:169] op_sel_hi:[1,0,1]
	v_mfma_f32_16x16x32_bf16 v[114:117], v[102:105], v[224:227], v[114:117]
	v_lshlrev_b32_e32 v142, 16, v20
	v_and_b32_e32 v143, 0xffff0000, v20
	v_lshlrev_b32_e32 v144, 16, v21
	s_waitcnt lgkmcnt(2)
	v_mfma_f32_16x16x32_bf16 v[138:141], v[106:109], v[242:245], v[138:141]
	v_and_b32_e32 v145, 0xffff0000, v21
	v_pk_fma_f32 v[118:119], v[118:119], v[0:1], v[166:167] op_sel_hi:[1,0,1]
	v_mov_b32_e32 v201, v154
	v_mfma_f32_16x16x32_bf16 v[114:117], v[98:101], v[242:245], v[114:117]
	v_mov_b32_e32 v0, v192
	v_mov_b32_e32 v202, v194
	s_waitcnt lgkmcnt(1)
	v_mfma_f32_16x16x32_bf16 v[142:145], v[110:113], v[212:215], v[142:145]
	s_cmp_gt_u32 s23, 33
	v_mfma_f32_16x16x32_bf16 v[118:121], v[102:105], v[212:215], v[118:121]
	v_mov_b32_e32 v147, v193
	v_mov_b32_e32 v148, v195
	v_mov_b32_e32 v146, v197
	s_waitcnt lgkmcnt(0)
	v_mfma_f32_16x16x32_bf16 v[142:145], v[106:109], v[216:219], v[142:145]
	v_mov_b32_e32 v149, v196
	v_mfma_f32_16x16x32_bf16 v[118:121], v[98:101], v[216:219], v[118:121]
	v_mov_b32_e32 v152, v192
	s_cbranch_scc1 .LBB0_533
	v_cvt_pk_bf16_f32 v148, v126, v127
	v_cvt_pk_bf16_f32 v149, v128, v129
	ds_write_b64 v199, v[148:149]
	v_cvt_pk_bf16_f32 v148, v122, v123
	v_cvt_pk_bf16_f32 v149, v124, v125
	ds_write_b64 v199, v[148:149] offset:2304
	v_cvt_pk_bf16_f32 v148, v114, v115
	v_cvt_pk_bf16_f32 v149, v116, v117
	ds_write_b64 v199, v[148:149] offset:4608
	v_cvt_pk_bf16_f32 v148, v118, v119
	v_cvt_pk_bf16_f32 v149, v120, v121
	ds_write_b64 v199, v[148:149] offset:6912

; #define LAS __attribute__((address_space(3)))
; template <bool GDN, int NT> __device__ __forceinline__ void scan_load(const Frame& F, int b, int h, int dir, const ScanLane& L, int s, ScanOps<NT>& o) {
;     ...
;     if (GDN) {
;         const char* base = (const char*)F.PG + (size_t)ud * 32768;
;         const char* bM = upin(base); const char* bB = upin(base + 8192); const char* bQ = upin(base + 16384); const char* bO = upin(base + 24576);
; #pragma unroll
;     ...
;     if (s < 36) {
; #pragma unroll
;         for (int t = 0; t < NT; ++t) *(LAS v2u*)(Sb + (16 * t + lr) * 72 + 16 * wq + 4 * lq) = pack4(S[t]); }
;     if (s == 21 || s == 3) asm volatile("s_waitcnt vmcnt(0)" ::: "memory");
;     else if (scan_needfin(s - 1)) { if (GDN) asm volatile("s_waitcnt vmcnt(14)" ::: "memory"); else asm volatile("s_waitcnt vmcnt(15)" ::: "memory"); }
;     else { if (GDN) asm volatile("s_waitcnt vmcnt(8)" ::: "memory"); else asm volatile("s_waitcnt vmcnt(9)" ::: "memory"); }
;     __syncthreads();
;     if (s > 0) {
;         const int sp = s - 1;
;         if (sp == 20 || sp == 2) { asm volatile("s_waitcnt vmcnt(0)" ::: "memory"); scan_fin_load<GDN>(F, b, h, dir, L, sp, PEND, fin); }
;         if (!nofin) scan_finish<GDN>(F, b, h, dir, L, sp, PEND, Oprev, fin);
;     }
;     if (s == 36) return false;
;     if (scan_needfin(s) && ko != 1 && ko != 3) scan_fin_load<GDN>(F, b, h, dir, L, s + 1, PEND, fin);
;     if (ko != 1 && ko != 2) scan_load<GDN, NT>(F, b, h, dir, L, s < 34 ? s + 2 : 35, ld);
;     const float gl = ((const LAS float*)(St + 4 * 80 * 72))[(dir ? (s < 4 ? 3 - s : 39 - s) : s) * 2 + dir];
;     f32x4 O[NT];
; #pragma unroll
;     for (int t = 0; t < NT; ++t) {
;         const LAS bf16_t* sp2 = Sb + (16 * t + lr) * 72 + 8 * lq;
;         const bf16x8 s0 = *(const LAS bf16x8*)sp2, s1 = *(const LAS bf16x8*)(sp2 + 32);
;         const f32x4 bv = unpack4(use.bv[t]), ov = unpack4(use.ov[t]);
;         if (GDN) {
;             f32x4 o = ov, sn = S[t] * gl + bv;
;             o = __builtin_amdgcn_mfma_f32_16x16x32_bf16(use.Qf[0], s0, o, 0, 0, 0); o = __builtin_amdgcn_mfma_f32_16x16x32_bf16(use.Qf[1], s1, o, 0, 0, 0);
;             sn = __builtin_amdgcn_mfma_f32_16x16x32_bf16(use.Mf[0], s0, sn, 0, 0, 0); sn = __builtin_amdgcn_mfma_f32_16x16x32_bf16(use.Mf[1], s1, sn, 0, 0, 0);
;             S[t] = sn; O[t] = o;
.LBB0_546:
	s_min_u32 s5, s3, 33
	s_add_i32 s8, s5, 2
	s_sub_i32 s5, 37, s5
	s_and_b64 s[6:7], s[90:91], exec
	s_cselect_b32 s5, s8, s5
	s_add_i32 s5, s5, s30
	s_lshl_b32 s5, s5, 1
	s_add_i32 s6, s5, s68
	s_ashr_i32 s7, s6, 31
	s_lshl_b64 s[6:7], s[6:7], 15
	s_add_u32 s6, s35, s6
	s_addc_u32 s7, s43, s7
	s_add_u32 s10, s6, 0x2000
	s_addc_u32 s11, s7, 0
	s_add_u32 s12, s6, 0x4000
	s_addc_u32 s13, s7, 0
	s_mov_b64 s[8:9], s[6:7]
	s_add_u32 s6, s6, 0x6000
	s_addc_u32 s7, s7, 0
	global_load_dwordx4 v[102:105], v201, s[8:9] nt
	global_load_dwordx4 v[110:113], v201, s[12:13] nt
	global_load_dwordx4 v[98:101], v201, s[8:9] offset:1024 nt
	global_load_dwordx4 v[106:109], v201, s[12:13] offset:1024 nt
	global_load_dwordx4 v[70:73], v0, s[10:11] nt
	global_load_dwordx4 v[66:69], v0, s[6:7] nt
	global_load_dwordx4 v[22:25], v0, s[10:11] offset:1024 nt
	global_load_dwordx4 v[18:21], v0, s[6:7] offset:1024 nt
	s_add_i32 s6, s4, 1
	s_and_b64 s[4:5], s[90:91], exec
	s_cselect_b32 s4, s3, s6
	s_lshl_b32 s4, s4, 3
	s_add_i32 s4, s34, s4
	v_mov_b32_e32 v0, s4
	ds_read_b32 v0, v0 offset:46080
	ds_read_b128 v[204:207], v200
	ds_read_b128 v[208:211], v200 offset:64
	ds_read_b128 v[212:215], v200 offset:2304
	ds_read_b128 v[216:219], v200 offset:2368
	ds_read_b128 v[224:227], v200 offset:4608
	ds_read_b128 v[242:245], v200 offset:4672
	v_lshlrev_b32_e32 v134, 16, v94
	v_and_b32_e32 v135, 0xffff0000, v94
	v_lshlrev_b32_e32 v94, 16, v95
	v_and_b32_e32 v95, 0xffff0000, v95
	v_lshlrev_b32_e32 v130, 16, v86
	v_and_b32_e32 v131, 0xffff0000, v86
	v_lshlrev_b32_e32 v132, 16, v87
	v_and_b32_e32 v133, 0xffff0000, v87
	s_waitcnt lgkmcnt(6)
	v_pk_fma_f32 v[128:129], v[128:129], v[0:1], v[94:95] op_sel_hi:[1,0,1]
	v_pk_fma_f32 v[126:127], v[126:127], v[0:1], v[134:135] op_sel_hi:[1,0,1]
	s_waitcnt lgkmcnt(5)
	v_mfma_f32_16x16x32_bf16 v[130:133], v[46:49], v[204:207], v[130:133]
	v_lshlrev_b32_e32 v94, 16, v96
	v_and_b32_e32 v95, 0xffff0000, v96
	v_lshlrev_b32_e32 v96, 16, v97
	v_mfma_f32_16x16x32_bf16 v[204:207], v[30:33], v[204:207], v[126:129]
	v_and_b32_e32 v97, 0xffff0000, v97
	v_lshlrev_b32_e32 v86, 16, v88
	v_and_b32_e32 v87, 0xffff0000, v88
	s_waitcnt lgkmcnt(4)
	v_mfma_f32_16x16x32_bf16 v[130:133], v[34:37], v[208:211], v[130:133]
	v_lshlrev_b32_e32 v88, 16, v89
	v_and_b32_e32 v89, 0xffff0000, v89
	v_pk_fma_f32 v[96:97], v[124:125], v[0:1], v[96:97] op_sel_hi:[1,0,1]
	v_mfma_f32_16x16x32_bf16 v[126:129], v[26:29], v[208:211], v[204:207]
	s_nop 2
	v_pk_fma_f32 v[94:95], v[122:123], v[0:1], v[94:95] op_sel_hi:[1,0,1]
	s_waitcnt lgkmcnt(3)
	v_mfma_f32_16x16x32_bf16 v[86:89], v[46:49], v[212:215], v[86:89]
	s_nop 0
	v_mfma_f32_16x16x32_bf16 v[204:207], v[30:33], v[212:215], v[94:97]
	s_waitcnt lgkmcnt(2)
	v_mfma_f32_16x16x32_bf16 v[134:137], v[34:37], v[216:219], v[86:89]
	s_nop 0
	v_lshlrev_b32_e32 v94, 16, v78
	v_and_b32_e32 v95, 0xffff0000, v78
	v_lshlrev_b32_e32 v78, 16, v79
	v_mfma_f32_16x16x32_bf16 v[122:125], v[26:29], v[216:219], v[204:207]
	ds_read_b128 v[212:215], v200 offset:6912
	ds_read_b128 v[216:219], v200 offset:6976
	s_nop 2
	v_and_b32_e32 v79, 0xffff0000, v79
	v_lshlrev_b32_e32 v86, 16, v74
	v_and_b32_e32 v87, 0xffff0000, v74
	v_lshlrev_b32_e32 v88, 16, v75
	v_and_b32_e32 v89, 0xffff0000, v75
	v_pk_fma_f32 v[96:97], v[116:117], v[0:1], v[78:79] op_sel_hi:[1,0,1]
	v_pk_fma_f32 v[94:95], v[114:115], v[0:1], v[94:95] op_sel_hi:[1,0,1]
	s_waitcnt lgkmcnt(3)
	v_mfma_f32_16x16x32_bf16 v[86:89], v[46:49], v[224:227], v[86:89]
	v_lshlrev_b32_e32 v78, 16, v80
	v_and_b32_e32 v79, 0xffff0000, v80
	v_lshlrev_b32_e32 v80, 16, v81
	v_mfma_f32_16x16x32_bf16 v[204:207], v[30:33], v[224:227], v[94:97]
	v_and_b32_e32 v81, 0xffff0000, v81
	v_lshlrev_b32_e32 v74, 16, v76
	v_and_b32_e32 v75, 0xffff0000, v76
	s_waitcnt lgkmcnt(2)
	v_mfma_f32_16x16x32_bf16 v[138:141], v[34:37], v[242:245], v[86:89]
	v_lshlrev_b32_e32 v76, 16, v77
	v_and_b32_e32 v77, 0xffff0000, v77
	v_pk_fma_f32 v[80:81], v[120:121], v[0:1], v[80:81] op_sel_hi:[1,0,1]
	v_mfma_f32_16x16x32_bf16 v[114:117], v[26:29], v[242:245], v[204:207]
	s_nop 2
	v_pk_fma_f32 v[78:79], v[118:119], v[0:1], v[78:79] op_sel_hi:[1,0,1]
	s_waitcnt lgkmcnt(1)
	v_mfma_f32_16x16x32_bf16 v[46:49], v[46:49], v[212:215], v[74:77]
	v_mfma_f32_16x16x32_bf16 v[204:207], v[30:33], v[212:215], v[78:81]
	s_waitcnt lgkmcnt(0)
	v_mfma_f32_16x16x32_bf16 v[142:145], v[34:37], v[216:219], v[46:49]
	v_mfma_f32_16x16x32_bf16 v[118:121], v[26:29], v[216:219], v[204:207]

; #define LAS __attribute__((address_space(3)))
; __device__ __forceinline__ v2u pack4(const f32x4 v) { v2u r; r.x = pk2(v[0], v[1]); r.y = pk2(v[2], v[3]); return r; }
; __device__ __forceinline__ f32x4 unpack4(const v2u w) { f32x4 r; r[0] = bflo(w.x); r[1] = bfhi(w.x); r[2] = bflo(w.y); r[3] = bfhi(w.y); return r; }
; __device__ __forceinline__ bool scan_needfin(int s) { return s >= 0 && s < 35 && !scan_first(s + 1) && s + 1 != 20 && s + 1 != 2; }
;     ...
;     if (s < 36) {
; #pragma unroll
;         for (int t = 0; t < NT; ++t) *(LAS v2u*)(Sb + (16 * t + lr) * 72 + 16 * wq + 4 * lq) = pack4(S[t]); }
;     if (s == 21 || s == 3) asm volatile("s_waitcnt vmcnt(0)" ::: "memory");
;     else if (scan_needfin(s - 1)) { if (GDN) asm volatile("s_waitcnt vmcnt(14)" ::: "memory"); else asm volatile("s_waitcnt vmcnt(15)" ::: "memory"); }
;     else { if (GDN) asm volatile("s_waitcnt vmcnt(8)" ::: "memory"); else asm volatile("s_waitcnt vmcnt(9)" ::: "memory"); }
;     __syncthreads();
;     if (s > 0) {
;         const int sp = s - 1;
;         if (sp == 20 || sp == 2) { asm volatile("s_waitcnt vmcnt(0)" ::: "memory"); scan_fin_load<GDN>(F, b, h, dir, L, sp, PEND, fin); }
;         if (!nofin) scan_finish<GDN>(F, b, h, dir, L, sp, PEND, Oprev, fin);
;     }
;     if (s == 36) return false;
;     if (scan_needfin(s) && ko != 1 && ko != 3) scan_fin_load<GDN>(F, b, h, dir, L, s + 1, PEND, fin);
;     if (ko != 1 && ko != 2) scan_load<GDN, NT>(F, b, h, dir, L, s < 34 ? s + 2 : 35, ld);
;     const float gl = ((const LAS float*)(St + 4 * 80 * 72))[(dir ? (s < 4 ? 3 - s : 39 - s) : s) * 2 + dir];
;     f32x4 O[NT];
; #pragma unroll
;     for (int t = 0; t < NT; ++t) {
;         const LAS bf16_t* sp2 = Sb + (16 * t + lr) * 72 + 8 * lq;
;         const bf16x8 s0 = *(const LAS bf16x8*)sp2, s1 = *(const LAS bf16x8*)(sp2 + 32);
;         const f32x4 bv = unpack4(use.bv[t]), ov = unpack4(use.ov[t]);
;         if (GDN) {
;             f32x4 o = ov, sn = S[t] * gl + bv;
;             o = __builtin_amdgcn_mfma_f32_16x16x32_bf16(use.Qf[0], s0, o, 0, 0, 0); o = __builtin_amdgcn_mfma_f32_16x16x32_bf16(use.Qf[1], s1, o, 0, 0, 0);
;             sn = __builtin_amdgcn_mfma_f32_16x16x32_bf16(use.Mf[0], s0, sn, 0, 0, 0); sn = __builtin_amdgcn_mfma_f32_16x16x32_bf16(use.Mf[1], s1, sn, 0, 0, 0);
;             S[t] = sn; O[t] = o;
.LBB0_571:
	s_add_i32 s12, s23, 3
	s_min_u32 s4, s12, 33
	s_add_i32 s6, s4, 2
	s_sub_i32 s7, 37, s4
	s_and_b64 s[4:5], s[90:91], exec
	s_cselect_b32 s4, s6, s7
	s_add_i32 s4, s4, s30
	s_lshl_b32 s4, s4, 1
	s_add_i32 s4, s4, s68
	s_ashr_i32 s5, s4, 31
	s_lshl_b64 s[4:5], s[4:5], 15
	s_add_u32 s4, s35, s4
	s_addc_u32 s5, s43, s5
	s_add_u32 s8, s4, 0x2000
	s_addc_u32 s9, s5, 0
	s_add_u32 s10, s4, 0x4000
	s_addc_u32 s11, s5, 0
	s_mov_b64 s[6:7], s[4:5]
	s_add_u32 s4, s4, 0x6000
	s_addc_u32 s5, s5, 0
	global_load_dwordx4 v[30:33], v34, s[6:7] nt
	global_load_dwordx4 v[46:49], v34, s[10:11] nt
	global_load_dwordx4 v[26:29], v34, s[6:7] offset:1024 nt
	s_nop 0
	global_load_dwordx4 v[34:37], v34, s[10:11] offset:1024 nt
	s_nop 0
	global_load_dwordx4 v[94:97], v0, s[8:9] nt
	global_load_dwordx4 v[86:89], v0, s[4:5] nt
	global_load_dwordx4 v[78:81], v0, s[8:9] offset:1024 nt
	global_load_dwordx4 v[74:77], v0, s[4:5] offset:1024 nt
	s_add_i32 s1, s1, s22
	s_and_b64 s[4:5], s[90:91], exec
	s_cselect_b32 s1, s12, s1
	s_lshl_b32 s4, s1, 3
	s_add_i32 s4, s34, s4
	v_mov_b32_e32 v0, s4
	ds_read_b32 v0, v0 offset:46080
	ds_read_b128 v[134:137], v200 offset:11520
	ds_read_b128 v[138:141], v200 offset:11584
	ds_read_b128 v[212:215], v200 offset:13824
	ds_read_b128 v[216:219], v200 offset:13888
	ds_read_b128 v[224:227], v200 offset:16128
	ds_read_b128 v[242:245], v200 offset:16192
	s_waitcnt vmcnt(63)
	v_lshlrev_b32_e32 v142, 16, v90
	v_and_b32_e32 v143, 0xffff0000, v90
	v_lshlrev_b32_e32 v144, 16, v91
	v_and_b32_e32 v145, 0xffff0000, v91
	s_waitcnt vmcnt(63)
	v_lshlrev_b32_e32 v130, 16, v82
	v_and_b32_e32 v131, 0xffff0000, v82
	v_lshlrev_b32_e32 v132, 16, v83
	v_and_b32_e32 v133, 0xffff0000, v83
	s_waitcnt lgkmcnt(6)
	v_pk_fma_f32 v[128:129], v[128:129], v[0:1], v[144:145] op_sel_hi:[1,0,1]
	v_pk_fma_f32 v[126:127], v[126:127], v[0:1], v[142:143] op_sel_hi:[1,0,1]
	s_waitcnt lgkmcnt(5)
	v_mfma_f32_16x16x32_bf16 v[130:133], v[58:61], v[134:137], v[130:133]
	v_lshlrev_b32_e32 v146, 16, v92
	v_and_b32_e32 v147, 0xffff0000, v92
	v_lshlrev_b32_e32 v148, 16, v93
	v_mfma_f32_16x16x32_bf16 v[126:129], v[42:45], v[134:137], v[126:129]
	v_and_b32_e32 v149, 0xffff0000, v93
	v_lshlrev_b32_e32 v134, 16, v84
	v_and_b32_e32 v135, 0xffff0000, v84
	s_waitcnt lgkmcnt(4)
	v_mfma_f32_16x16x32_bf16 v[130:133], v[50:53], v[138:141], v[130:133]
	v_lshlrev_b32_e32 v136, 16, v85
	v_and_b32_e32 v137, 0xffff0000, v85
	v_pk_fma_f32 v[124:125], v[124:125], v[0:1], v[148:149] op_sel_hi:[1,0,1]
	v_mfma_f32_16x16x32_bf16 v[126:129], v[38:41], v[138:141], v[126:129]
	v_pk_fma_f32 v[122:123], v[122:123], v[0:1], v[146:147] op_sel_hi:[1,0,1]
	s_waitcnt vmcnt(63)
	v_lshlrev_b32_e32 v150, 16, v62
	s_waitcnt lgkmcnt(3)
	v_mfma_f32_16x16x32_bf16 v[134:137], v[58:61], v[212:215], v[134:137]
	v_and_b32_e32 v151, 0xffff0000, v62
	v_lshlrev_b32_e32 v152, 16, v63
	v_and_b32_e32 v153, 0xffff0000, v63
	v_mfma_f32_16x16x32_bf16 v[122:125], v[42:45], v[212:215], v[122:125]
	s_waitcnt vmcnt(63)
	v_lshlrev_b32_e32 v138, 16, v54
	v_and_b32_e32 v139, 0xffff0000, v54
	v_lshlrev_b32_e32 v140, 16, v55
	s_waitcnt lgkmcnt(2)
	v_mfma_f32_16x16x32_bf16 v[134:137], v[50:53], v[216:219], v[134:137]
	v_and_b32_e32 v141, 0xffff0000, v55
	v_pk_fma_f32 v[116:117], v[116:117], v[0:1], v[152:153] op_sel_hi:[1,0,1]
	v_pk_fma_f32 v[114:115], v[114:115], v[0:1], v[150:151] op_sel_hi:[1,0,1]
	v_mfma_f32_16x16x32_bf16 v[122:125], v[38:41], v[216:219], v[122:125]
	ds_read_b128 v[212:215], v200 offset:18432
	ds_read_b128 v[216:219], v200 offset:18496
	v_lshlrev_b32_e32 v166, 16, v64
	v_and_b32_e32 v167, 0xffff0000, v64
	s_waitcnt lgkmcnt(3)
	v_mfma_f32_16x16x32_bf16 v[138:141], v[58:61], v[224:227], v[138:141]
	v_lshlrev_b32_e32 v168, 16, v65
	v_and_b32_e32 v169, 0xffff0000, v65
	v_pk_fma_f32 v[120:121], v[120:121], v[0:1], v[168:169] op_sel_hi:[1,0,1]
	v_mfma_f32_16x16x32_bf16 v[114:117], v[42:45], v[224:227], v[114:117]
	v_lshlrev_b32_e32 v142, 16, v56
	v_and_b32_e32 v143, 0xffff0000, v56
	v_lshlrev_b32_e32 v144, 16, v57
	s_waitcnt lgkmcnt(2)
	v_mfma_f32_16x16x32_bf16 v[138:141], v[50:53], v[242:245], v[138:141]
	v_and_b32_e32 v145, 0xffff0000, v57
	v_pk_fma_f32 v[118:119], v[118:119], v[0:1], v[166:167] op_sel_hi:[1,0,1]
	v_mov_b32_e32 v0, v192
	v_mfma_f32_16x16x32_bf16 v[114:117], v[38:41], v[242:245], v[114:117]
	s_cmp_gt_u32 s23, 31
	s_waitcnt lgkmcnt(1)
	v_mfma_f32_16x16x32_bf16 v[142:145], v[58:61], v[212:215], v[142:145]
	v_mfma_f32_16x16x32_bf16 v[118:121], v[42:45], v[212:215], v[118:121]
	v_mov_b32_e32 v146, v154
	v_mov_b32_e32 v149, v197
	v_mov_b32_e32 v148, v192
	s_waitcnt lgkmcnt(0)
	v_mfma_f32_16x16x32_bf16 v[142:145], v[50:53], v[216:219], v[142:145]
	v_mov_b32_e32 v147, v194
	v_mfma_f32_16x16x32_bf16 v[118:121], v[38:41], v[216:219], v[118:121]
	v_mov_b32_e32 v150, v196
	v_mov_b32_e32 v151, v193
	v_mov_b32_e32 v152, v195
	s_cbranch_scc1 .LBB0_582
	v_cvt_pk_bf16_f32 v150, v126, v127
	v_cvt_pk_bf16_f32 v151, v128, v129
	ds_write_b64 v199, v[150:151]
	v_cvt_pk_bf16_f32 v150, v122, v123
	v_cvt_pk_bf16_f32 v151, v124, v125
	ds_write_b64 v199, v[150:151] offset:2304
	v_cvt_pk_bf16_f32 v150, v114, v115
	v_cvt_pk_bf16_f32 v151, v116, v117
	ds_write_b64 v199, v[150:151] offset:4608
	v_cvt_pk_bf16_f32 v150, v118, v119
	v_cvt_pk_bf16_f32 v151, v120, v121
	ds_write_b64 v199, v[150:151] offset:6912
	s_sub_i32 s4, s23, 17
	s_cmp_gt_u32 s4, 14
	s_mov_b64 s[10:11], -1
	s_cbranch_scc1 .LBB0_583

; #define LAS __attribute__((address_space(3)))
; template <bool GDN, int NT> __device__ __forceinline__ void scan_load(const Frame& F, int b, int h, int dir, const ScanLane& L, int s, ScanOps<NT>& o) {
;     ...
;     if (GDN) {
;         const char* base = (const char*)F.PG + (size_t)ud * 32768;
;         const char* bM = upin(base); const char* bB = upin(base + 8192); const char* bQ = upin(base + 16384); const char* bO = upin(base + 24576);
; #pragma unroll
;     ...
;     if (s < 36) {
; #pragma unroll
;         for (int t = 0; t < NT; ++t) *(LAS v2u*)(Sb + (16 * t + lr) * 72 + 16 * wq + 4 * lq) = pack4(S[t]); }
;     if (s == 21 || s == 3) asm volatile("s_waitcnt vmcnt(0)" ::: "memory");
;     else if (scan_needfin(s - 1)) { if (GDN) asm volatile("s_waitcnt vmcnt(14)" ::: "memory"); else asm volatile("s_waitcnt vmcnt(15)" ::: "memory"); }
;     else { if (GDN) asm volatile("s_waitcnt vmcnt(8)" ::: "memory"); else asm volatile("s_waitcnt vmcnt(9)" ::: "memory"); }
;     __syncthreads();
;     if (s > 0) {
;         const int sp = s - 1;
;         if (sp == 20 || sp == 2) { asm volatile("s_waitcnt vmcnt(0)" ::: "memory"); scan_fin_load<GDN>(F, b, h, dir, L, sp, PEND, fin); }
;         if (!nofin) scan_finish<GDN>(F, b, h, dir, L, sp, PEND, Oprev, fin);
;     }
;     if (s == 36) return false;
;     if (scan_needfin(s) && ko != 1 && ko != 3) scan_fin_load<GDN>(F, b, h, dir, L, s + 1, PEND, fin);
;     if (ko != 1 && ko != 2) scan_load<GDN, NT>(F, b, h, dir, L, s < 34 ? s + 2 : 35, ld);
;     const float gl = ((const LAS float*)(St + 4 * 80 * 72))[(dir ? (s < 4 ? 3 - s : 39 - s) : s) * 2 + dir];
;     f32x4 O[NT];
; #pragma unroll
;     for (int t = 0; t < NT; ++t) {
;         const LAS bf16_t* sp2 = Sb + (16 * t + lr) * 72 + 8 * lq;
;         const bf16x8 s0 = *(const LAS bf16x8*)sp2, s1 = *(const LAS bf16x8*)(sp2 + 32);
;         const f32x4 bv = unpack4(use.bv[t]), ov = unpack4(use.ov[t]);
;         if (GDN) {
;             f32x4 o = ov, sn = S[t] * gl + bv;
;             o = __builtin_amdgcn_mfma_f32_16x16x32_bf16(use.Qf[0], s0, o, 0, 0, 0); o = __builtin_amdgcn_mfma_f32_16x16x32_bf16(use.Qf[1], s1, o, 0, 0, 0);
;             sn = __builtin_amdgcn_mfma_f32_16x16x32_bf16(use.Mf[0], s0, sn, 0, 0, 0); sn = __builtin_amdgcn_mfma_f32_16x16x32_bf16(use.Mf[1], s1, sn, 0, 0, 0);
;             S[t] = sn; O[t] = o;
.LBB0_588:
	s_min_u32 s0, s3, 33
	s_add_i32 s4, s0, 2
	s_sub_i32 s5, 37, s0
	s_and_b64 s[0:1], s[90:91], exec
	s_cselect_b32 s0, s4, s5
	s_add_i32 s0, s0, s30
	s_lshl_b32 s0, s0, 1
	s_add_i32 s0, s0, s68
	s_ashr_i32 s1, s0, 31
	s_lshl_b64 s[0:1], s[0:1], 15
	s_add_u32 s0, s35, s0
	s_addc_u32 s1, s43, s1
	s_add_u32 s6, s0, 0x2000
	s_addc_u32 s7, s1, 0
	s_add_u32 s8, s0, 0x4000
	s_addc_u32 s9, s1, 0
	s_mov_b64 s[4:5], s[0:1]
	s_add_u32 s0, s0, 0x6000
	s_addc_u32 s1, s1, 0
	global_load_dwordx4 v[42:45], v146, s[4:5] nt
	global_load_dwordx4 v[58:61], v146, s[8:9] nt
	global_load_dwordx4 v[38:41], v146, s[4:5] offset:1024 nt
	global_load_dwordx4 v[50:53], v146, s[8:9] offset:1024 nt
	global_load_dwordx4 v[90:93], v0, s[6:7] nt
	global_load_dwordx4 v[82:85], v0, s[0:1] nt
	global_load_dwordx4 v[62:65], v0, s[6:7] offset:1024 nt
	global_load_dwordx4 v[54:57], v0, s[0:1] offset:1024 nt
	s_add_i32 s4, s22, 38
	s_and_b64 s[0:1], s[90:91], exec
	s_cselect_b32 s0, s3, s4
	s_lshl_b32 s0, s0, 3
	s_add_i32 s0, s34, s0
	v_mov_b32_e32 v0, s0
	ds_read_b32 v0, v0 offset:46080
	ds_read_b128 v[134:137], v200
	ds_read_b128 v[138:141], v200 offset:64
	ds_read_b128 v[212:215], v200 offset:2304
	ds_read_b128 v[216:219], v200 offset:2368
	ds_read_b128 v[224:227], v200 offset:4608
	ds_read_b128 v[242:245], v200 offset:4672
	v_lshlrev_b32_e32 v142, 16, v70
	v_and_b32_e32 v143, 0xffff0000, v70
	v_lshlrev_b32_e32 v70, 16, v71
	v_and_b32_e32 v71, 0xffff0000, v71
	v_lshlrev_b32_e32 v130, 16, v66
	v_and_b32_e32 v131, 0xffff0000, v66
	v_lshlrev_b32_e32 v132, 16, v67
	v_and_b32_e32 v133, 0xffff0000, v67
	s_waitcnt lgkmcnt(6)
	v_pk_fma_f32 v[128:129], v[128:129], v[0:1], v[70:71] op_sel_hi:[1,0,1]
	v_pk_fma_f32 v[126:127], v[126:127], v[0:1], v[142:143] op_sel_hi:[1,0,1]
	s_waitcnt lgkmcnt(5)
	v_mfma_f32_16x16x32_bf16 v[130:133], v[110:113], v[134:137], v[130:133]
	v_lshlrev_b32_e32 v66, 16, v68
	v_and_b32_e32 v67, 0xffff0000, v68
	v_lshlrev_b32_e32 v68, 16, v69
	v_mfma_f32_16x16x32_bf16 v[126:129], v[102:105], v[134:137], v[126:129]
	v_and_b32_e32 v69, 0xffff0000, v69
	v_lshlrev_b32_e32 v70, 16, v72
	v_and_b32_e32 v71, 0xffff0000, v72
	s_waitcnt lgkmcnt(4)
	v_mfma_f32_16x16x32_bf16 v[130:133], v[106:109], v[138:141], v[130:133]
	v_lshlrev_b32_e32 v72, 16, v73
	v_and_b32_e32 v73, 0xffff0000, v73
	v_pk_fma_f32 v[72:73], v[124:125], v[0:1], v[72:73] op_sel_hi:[1,0,1]
	v_mfma_f32_16x16x32_bf16 v[126:129], v[98:101], v[138:141], v[126:129]
	v_pk_fma_f32 v[70:71], v[122:123], v[0:1], v[70:71] op_sel_hi:[1,0,1]
	s_waitcnt lgkmcnt(3)
	v_mfma_f32_16x16x32_bf16 v[66:69], v[110:113], v[212:215], v[66:69]
	s_waitcnt lgkmcnt(2)
	v_mfma_f32_16x16x32_bf16 v[134:137], v[106:109], v[216:219], v[66:69]
	v_mfma_f32_16x16x32_bf16 v[66:69], v[102:105], v[212:215], v[70:73]
	v_lshlrev_b32_e32 v138, 16, v18
	v_and_b32_e32 v139, 0xffff0000, v18
	v_lshlrev_b32_e32 v140, 16, v19
	v_mfma_f32_16x16x32_bf16 v[122:125], v[98:101], v[216:219], v[66:69]
	ds_read_b128 v[212:215], v200 offset:6912
	ds_read_b128 v[216:219], v200 offset:6976
	s_nop 3
	v_lshlrev_b32_e32 v142, 16, v22
	v_and_b32_e32 v143, 0xffff0000, v22
	v_lshlrev_b32_e32 v22, 16, v23
	v_and_b32_e32 v23, 0xffff0000, v23
	v_and_b32_e32 v141, 0xffff0000, v19
	v_pk_fma_f32 v[116:117], v[116:117], v[0:1], v[22:23] op_sel_hi:[1,0,1]
	v_pk_fma_f32 v[114:115], v[114:115], v[0:1], v[142:143] op_sel_hi:[1,0,1]
	s_waitcnt lgkmcnt(3)
	v_mfma_f32_16x16x32_bf16 v[138:141], v[110:113], v[224:227], v[138:141]
	v_lshlrev_b32_e32 v18, 16, v20
	v_and_b32_e32 v19, 0xffff0000, v20
	v_lshlrev_b32_e32 v20, 16, v21
	v_mfma_f32_16x16x32_bf16 v[66:69], v[102:105], v[224:227], v[114:117]
	v_and_b32_e32 v21, 0xffff0000, v21
	v_lshlrev_b32_e32 v22, 16, v24
	v_and_b32_e32 v23, 0xffff0000, v24
	s_waitcnt lgkmcnt(2)
	v_mfma_f32_16x16x32_bf16 v[138:141], v[106:109], v[242:245], v[138:141]
	v_lshlrev_b32_e32 v24, 16, v25
	v_and_b32_e32 v25, 0xffff0000, v25
	v_pk_fma_f32 v[24:25], v[120:121], v[0:1], v[24:25] op_sel_hi:[1,0,1]
	v_mfma_f32_16x16x32_bf16 v[114:117], v[98:101], v[242:245], v[66:69]
	s_nop 2
	v_pk_fma_f32 v[22:23], v[118:119], v[0:1], v[22:23] op_sel_hi:[1,0,1]
	s_waitcnt lgkmcnt(1)
	v_mfma_f32_16x16x32_bf16 v[18:21], v[110:113], v[212:215], v[18:21]
	s_waitcnt lgkmcnt(0)
	v_mfma_f32_16x16x32_bf16 v[142:145], v[106:109], v[216:219], v[18:21]
	v_mfma_f32_16x16x32_bf16 v[18:21], v[102:105], v[212:215], v[22:25]
	v_mfma_f32_16x16x32_bf16 v[118:121], v[98:101], v[216:219], v[18:21]

; __device__ __forceinline__ void mlstm_prep_unit(const Frame& F, int l, int u) {
;     ...
;     if (w < 2) {
;         const int d = w, p = d ? 63 - lane : lane;
;         const int step_of = d ? (cidx < 4 ? 3 - cidx : 39 - cidx) : cidx; float mprev = 0.f;
;         for (int s = 0; s < step_of; ++s) { const int ci = d ? (s < 4 ? 3 - s : 39 - s) : s; mprev = fmaxf(chS[d * 72 + ci * 2] + mprev, chS[d * 72 + ci * 2 + 1]); }
.LBB0_710:
	s_or_b64 exec, exec, s[10:11]
	s_cmp_gt_i32 s3, 1
	s_waitcnt lgkmcnt(0)
	s_barrier
	s_cbranch_scc1 .LBB0_722
	s_cmp_gt_i32 s4, 3
	s_cselect_b32 s5, 39, 3
	s_sub_i32 s5, s5, s4
	s_cmp_eq_u32 s3, 0
	s_cselect_b64 vcc, -1, 0
	s_cselect_b32 s4, s4, s5
	v_mov_b32_e32 v6, 0
	s_cmp_lt_i32 s4, 1
	s_cbranch_scc1 .LBB0_719
	s_mul_i32 s5, s3, 0x120
	s_add_i32 s5, s5, 0x11320
	v_cmp_gt_u32_e64 s[6:7], 4, v62
	v_mov_b32_e32 v0, 39
	s_nop 1
	v_cndmask_b32_e64 v0, v0, 3, s[6:7]
	v_sub_u32_e32 v0, v0, v62
	v_cndmask_b32_e32 v0, v0, v62, vcc
	v_lshl_add_u32 v0, v0, 3, s5
	ds_read_b64 v[4:5], v0
	s_waitcnt lgkmcnt(0)
	v_readlane_b32 s6, v4, 0
	v_readlane_b32 s7, v5, 0
	v_readlane_b32 s8, v4, 1
	v_readlane_b32 s9, v5, 1
	v_add_f32_e32 v6, s6, v6
	v_max_f32_e32 v6, s7, v6
	s_cmp_eq_u32 s4, 1
	s_cbranch_scc1 .LBB0_719
	v_readlane_b32 s6, v4, 2
	v_readlane_b32 s7, v5, 2
	v_add_f32_e32 v6, s8, v6
	v_max_f32_e32 v6, s9, v6
	s_cmp_eq_u32 s4, 2
	s_cbranch_scc1 .LBB0_719
	v_readlane_b32 s8, v4, 3
	v_readlane_b32 s9, v5, 3
	v_add_f32_e32 v6, s6, v6
	v_max_f32_e32 v6, s7, v6
	s_cmp_eq_u32 s4, 3
	s_cbranch_scc1 .LBB0_719
	v_readlane_b32 s6, v4, 4
	v_readlane_b32 s7, v5, 4
	v_add_f32_e32 v6, s8, v6
	v_max_f32_e32 v6, s9, v6
	s_cmp_eq_u32 s4, 4
	s_cbranch_scc1 .LBB0_719
	v_readlane_b32 s8, v4, 5
	v_readlane_b32 s9, v5, 5
	v_add_f32_e32 v6, s6, v6
	v_max_f32_e32 v6, s7, v6
	s_cmp_eq_u32 s4, 5
	s_cbranch_scc1 .LBB0_719
	v_readlane_b32 s6, v4, 6
	v_readlane_b32 s7, v5, 6
	v_add_f32_e32 v6, s8, v6
	v_max_f32_e32 v6, s9, v6
	s_cmp_eq_u32 s4, 6
	s_cbranch_scc1 .LBB0_719
	v_readlane_b32 s8, v4, 7
	v_readlane_b32 s9, v5, 7
	v_add_f32_e32 v6, s6, v6
	v_max_f32_e32 v6, s7, v6
	s_cmp_eq_u32 s4, 7
	s_cbranch_scc1 .LBB0_719
	v_readlane_b32 s6, v4, 8
	v_readlane_b32 s7, v5, 8
	v_add_f32_e32 v6, s8, v6
	v_max_f32_e32 v6, s9, v6
	s_cmp_eq_u32 s4, 8
	s_cbranch_scc1 .LBB0_719
	v_readlane_b32 s8, v4, 9
	v_readlane_b32 s9, v5, 9
	v_add_f32_e32 v6, s6, v6
	v_max_f32_e32 v6, s7, v6
	s_cmp_eq_u32 s4, 9
	s_cbranch_scc1 .LBB0_719
	v_readlane_b32 s6, v4, 10
	v_readlane_b32 s7, v5, 10
	v_add_f32_e32 v6, s8, v6
	v_max_f32_e32 v6, s9, v6
	s_cmp_eq_u32 s4, 10
	s_cbranch_scc1 .LBB0_719
	v_readlane_b32 s8, v4, 11
	v_readlane_b32 s9, v5, 11
	v_add_f32_e32 v6, s6, v6
	v_max_f32_e32 v6, s7, v6
	s_cmp_eq_u32 s4, 11
	s_cbranch_scc1 .LBB0_719
	v_readlane_b32 s6, v4, 12
	v_readlane_b32 s7, v5, 12
	v_add_f32_e32 v6, s8, v6
	v_max_f32_e32 v6, s9, v6
	s_cmp_eq_u32 s4, 12
	s_cbranch_scc1 .LBB0_719
	v_readlane_b32 s8, v4, 13
	v_readlane_b32 s9, v5, 13
	v_add_f32_e32 v6, s6, v6
	v_max_f32_e32 v6, s7, v6
	s_cmp_eq_u32 s4, 13
	s_cbranch_scc1 .LBB0_719
	v_readlane_b32 s6, v4, 14
	v_readlane_b32 s7, v5, 14
	v_add_f32_e32 v6, s8, v6
	v_max_f32_e32 v6, s9, v6
	s_cmp_eq_u32 s4, 14
	s_cbranch_scc1 .LBB0_719
	v_readlane_b32 s8, v4, 15
	v_readlane_b32 s9, v5, 15
	v_add_f32_e32 v6, s6, v6
	v_max_f32_e32 v6, s7, v6
	s_cmp_eq_u32 s4, 15
	s_cbranch_scc1 .LBB0_719
	v_readlane_b32 s6, v4, 16
	v_readlane_b32 s7, v5, 16
	v_add_f32_e32 v6, s8, v6
	v_max_f32_e32 v6, s9, v6
	s_cmp_eq_u32 s4, 16
	s_cbranch_scc1 .LBB0_719
	v_readlane_b32 s8, v4, 17
	v_readlane_b32 s9, v5, 17
	v_add_f32_e32 v6, s6, v6
	v_max_f32_e32 v6, s7, v6
	s_cmp_eq_u32 s4, 17
	s_cbranch_scc1 .LBB0_719
	v_readlane_b32 s6, v4, 18
	v_readlane_b32 s7, v5, 18
	v_add_f32_e32 v6, s8, v6
	v_max_f32_e32 v6, s9, v6
	s_cmp_eq_u32 s4, 18
	s_cbranch_scc1 .LBB0_719
	v_readlane_b32 s8, v4, 19
	v_readlane_b32 s9, v5, 19
	v_add_f32_e32 v6, s6, v6
	v_max_f32_e32 v6, s7, v6
	s_cmp_eq_u32 s4, 19
	s_cbranch_scc1 .LBB0_719
	v_readlane_b32 s6, v4, 20
	v_readlane_b32 s7, v5, 20
	v_add_f32_e32 v6, s8, v6
	v_max_f32_e32 v6, s9, v6
	s_cmp_eq_u32 s4, 20
	s_cbranch_scc1 .LBB0_719
	v_readlane_b32 s8, v4, 21
	v_readlane_b32 s9, v5, 21
	v_add_f32_e32 v6, s6, v6
	v_max_f32_e32 v6, s7, v6
	s_cmp_eq_u32 s4, 21
	s_cbranch_scc1 .LBB0_719
	v_readlane_b32 s6, v4, 22
	v_readlane_b32 s7, v5, 22
	v_add_f32_e32 v6, s8, v6
	v_max_f32_e32 v6, s9, v6
	s_cmp_eq_u32 s4, 22
	s_cbranch_scc1 .LBB0_719
	v_readlane_b32 s8, v4, 23
	v_readlane_b32 s9, v5, 23
	v_add_f32_e32 v6, s6, v6
	v_max_f32_e32 v6, s7, v6
	s_cmp_eq_u32 s4, 23
	s_cbranch_scc1 .LBB0_719
	v_readlane_b32 s6, v4, 24
	v_readlane_b32 s7, v5, 24
	v_add_f32_e32 v6, s8, v6
	v_max_f32_e32 v6, s9, v6
	s_cmp_eq_u32 s4, 24
	s_cbranch_scc1 .LBB0_719
	v_readlane_b32 s8, v4, 25
	v_readlane_b32 s9, v5, 25
	v_add_f32_e32 v6, s6, v6
	v_max_f32_e32 v6, s7, v6
	s_cmp_eq_u32 s4, 25
	s_cbranch_scc1 .LBB0_719
	v_readlane_b32 s6, v4, 26
	v_readlane_b32 s7, v5, 26
	v_add_f32_e32 v6, s8, v6
	v_max_f32_e32 v6, s9, v6
	s_cmp_eq_u32 s4, 26
	s_cbranch_scc1 .LBB0_719
	v_readlane_b32 s8, v4, 27
	v_readlane_b32 s9, v5, 27
	v_add_f32_e32 v6, s6, v6
	v_max_f32_e32 v6, s7, v6
	s_cmp_eq_u32 s4, 27
	s_cbranch_scc1 .LBB0_719
	v_readlane_b32 s6, v4, 28
	v_readlane_b32 s7, v5, 28
	v_add_f32_e32 v6, s8, v6
	v_max_f32_e32 v6, s9, v6
	s_cmp_eq_u32 s4, 28
	s_cbranch_scc1 .LBB0_719
	v_readlane_b32 s8, v4, 29
	v_readlane_b32 s9, v5, 29
	v_add_f32_e32 v6, s6, v6
	v_max_f32_e32 v6, s7, v6
	s_cmp_eq_u32 s4, 29
	s_cbranch_scc1 .LBB0_719
	v_readlane_b32 s6, v4, 30
	v_readlane_b32 s7, v5, 30
	v_add_f32_e32 v6, s8, v6
	v_max_f32_e32 v6, s9, v6
	s_cmp_eq_u32 s4, 30
	s_cbranch_scc1 .LBB0_719
	v_readlane_b32 s8, v4, 31
	v_readlane_b32 s9, v5, 31
	v_add_f32_e32 v6, s6, v6
	v_max_f32_e32 v6, s7, v6
	s_cmp_eq_u32 s4, 31
	s_cbranch_scc1 .LBB0_719
	v_readlane_b32 s6, v4, 32
	v_readlane_b32 s7, v5, 32
	v_add_f32_e32 v6, s8, v6
	v_max_f32_e32 v6, s9, v6
	s_cmp_eq_u32 s4, 32
	s_cbranch_scc1 .LBB0_719
	v_readlane_b32 s8, v4, 33
	v_readlane_b32 s9, v5, 33
	v_add_f32_e32 v6, s6, v6
	v_max_f32_e32 v6, s7, v6
	s_cmp_eq_u32 s4, 33
	s_cbranch_scc1 .LBB0_719
	v_readlane_b32 s6, v4, 34
	v_readlane_b32 s7, v5, 34
	v_add_f32_e32 v6, s8, v6
	v_max_f32_e32 v6, s9, v6
	s_cmp_eq_u32 s4, 34
	s_cbranch_scc1 .LBB0_719
	s_nop 1
	v_add_f32_e32 v6, s6, v6
	v_max_f32_e32 v6, s7, v6
; __device__ __forceinline__ float fexp(float x) { return __builtin_amdgcn_exp2f(x * 1.4426950408889634f); }
; __device__ __forceinline__ void mlstm_prep_unit(const Frame& F, int l, int u) {
;     ...
;         const float ig = igS[d * 64 + p]; float bp = lfS[d * 64 + p];
; #pragma unroll
;         for (int off = 1; off < 64; off <<= 1) { const float y = __shfl_up(bp, off); if (lane >= off) bp += y; }
;         float mxp = ig - bp;
; #pragma unroll
;         for (int off = 1; off < 64; off <<= 1) { const float y = __shfl_up(mxp, off); if (lane >= off) mxp = fmaxf(mxp, y); }
;         const float mxall = __shfl(mxp, 63), bl = __shfl(bp, 63);
;         const float dmax = bp + mxp, wsmax = bl + mxall;
;         const float mnew = fmaxf(bl + mprev, wsmax), cd = fexp(bl + mprev - mnew), e2 = fexp(wsmax - mnew);
;         const float mt = fmaxf(bp + mprev, dmax);
;         bS[d * 64 + p] = bp; dmS[d * 64 + p] = dmax; rS[d * 64 + p] = fexp(dmax - mt); flS[d * 64 + p] = fexp(-mt);
;         eS[d * 64 + p] = fexp(bl - bp + ig - wsmax) * e2;
;         const int ud = u * 2 + d; F.WI[ud * 64 + p] = 0.125f * fexp(bp + mprev - mt); if (lane == 0) F.GLM[ud] = cd; }
.LBB0_719:
	v_xor_b32_e32 v0, 63, v62
	v_cndmask_b32_e32 v0, v0, v62, vcc
	v_lshlrev_b32_e32 v4, 2, v0
	v_lshl_or_b32 v4, s3, 8, v4
	v_add_u32_e32 v7, 0, v4
	v_add_u32_e32 v4, 0x10500, v7
	ds_read_b32 v8, v4
	v_add_u32_e32 v4, 0x10700, v7
	ds_read_b32 v4, v4
	v_add_u32_e32 v15, 0x10900, v7
	s_lshl_b32 s4, s1, 1
	v_cmp_eq_u32_e32 vcc, 0, v62
	s_add_i32 s10, s3, s4
	v_readlane_b32 s4, v254, 52
	v_readlane_b32 s5, v254, 53
	s_waitcnt lgkmcnt(0)
	v_mov_b32_e32 v14, v4
	s_nop 1
	v_add_f32_dpp v14, v14, v14 row_shr:1 row_mask:0xf bank_mask:0xf
	s_nop 1
	v_add_f32_dpp v14, v14, v14 row_shr:2 row_mask:0xf bank_mask:0xf
	s_nop 1
	v_add_f32_dpp v14, v14, v14 row_shr:4 row_mask:0xf bank_mask:0xf
	s_nop 1
	v_add_f32_dpp v14, v14, v14 row_shr:8 row_mask:0xf bank_mask:0xf
	s_nop 1
	v_add_f32_dpp v14, v14, v14 row_bcast:15 row_mask:0xa bank_mask:0xf
	s_nop 1
	v_add_f32_dpp v14, v14, v14 row_bcast:31 row_mask:0xc bank_mask:0xf
	v_sub_f32_e32 v4, v8, v14
	ds_write_b32 v15, v14
	v_add_u32_e32 v15, 0x10b00, v7
	s_nop 1
	v_max_f32_dpp v4, v4, v4 row_shr:1 row_mask:0xf bank_mask:0xf
	s_nop 1
	v_max_f32_dpp v4, v4, v4 row_shr:2 row_mask:0xf bank_mask:0xf
	s_nop 1
	v_max_f32_dpp v4, v4, v4 row_shr:4 row_mask:0xf bank_mask:0xf
	s_nop 1
	v_max_f32_dpp v4, v4, v4 row_shr:8 row_mask:0xf bank_mask:0xf
	s_nop 1
	v_max_f32_dpp v4, v4, v4 row_bcast:15 row_mask:0xa bank_mask:0xf
	s_nop 1
	v_max_f32_dpp v4, v4, v4 row_bcast:31 row_mask:0xc bank_mask:0xf
	s_nop 0
	v_readlane_b32 s8, v14, 63
	v_readlane_b32 s9, v4, 63
	v_add_f32_e32 v11, v14, v4
	ds_write_b32 v15, v11
	v_add_u32_e32 v15, 0x10d00, v7
	v_mov_b32_e32 v10, s8
	v_mov_b32_e32 v9, s9
	s_waitcnt lgkmcnt(2)
	v_add_f32_e32 v4, v6, v10
	v_add_f32_e32 v6, v6, v14
	s_waitcnt lgkmcnt(1)
	v_add_f32_e32 v9, v9, v10
	v_max_f32_e32 v13, v6, v11
	v_sub_f32_e32 v10, v10, v14
	v_max_f32_e32 v5, v4, v9
	v_sub_f32_e32 v11, v11, v13
	v_add_f32_e32 v8, v8, v10
	v_sub_f32_e32 v12, v9, v5
	v_mul_f32_e32 v11, 0x3fb8aa3b, v11
	v_sub_f32_e32 v8, v8, v9
	v_mul_f32_e32 v12, 0x3fb8aa3b, v12
	v_exp_f32_e32 v11, v11
	v_mul_f32_e32 v8, 0x3fb8aa3b, v8
	v_sub_f32_e32 v6, v6, v13
	v_exp_f32_e32 v12, v12
	v_exp_f32_e32 v8, v8
	v_mul_f32_e32 v6, 0x3fb8aa3b, v6
	v_exp_f32_e32 v6, v6
	ds_write_b32 v15, v11
	v_mul_f32_e32 v11, 0xbfb8aa3b, v13
	v_exp_f32_e32 v11, v11
	v_add_u32_e32 v15, 0x10f00, v7
	v_mul_f32_e32 v8, v8, v12
	v_add_u32_e32 v7, 0x11100, v7
	ds_write_b32 v7, v8
	v_mul_f32_e32 v8, 0x3e000000, v6
	v_lshl_or_b32 v6, s10, 6, v0
	v_ashrrev_i32_e32 v7, 31, v6
	v_lshl_add_u64 v[6:7], v[6:7], 2, s[4:5]
	ds_write_b32 v15, v11
	global_store_dword v[6:7], v8, off
	s_and_saveexec_b64 s[12:13], vcc
	s_cbranch_execz .LBB0_721
	v_sub_f32_e32 v0, v4, v5
	v_mul_f32_e32 v0, 0x3fb8aa3b, v0
	s_ashr_i32 s11, s10, 31
	v_exp_f32_e32 v0, v0
	s_lshl_b64 s[4:5], s[10:11], 2
	v_readlane_b32 s6, v254, 48
	v_readlane_b32 s7, v254, 49
	s_add_u32 s4, s6, s4
	s_addc_u32 s5, s7, s5
	global_store_dword v1, v0, s[4:5]
